# UP K-loop: B0 fragment LDS reads issued one phase earlier (in the MFMA sections of phases 4/8) to balance the load sections
# speedup vs baseline: 1.0659x; 1.0023x over previous
; #define PG8_STAGE(bufoff, gbase, voff) do { _Pragma("unroll") for (int _i = 0; _i < 2; ++_i) \
;         __builtin_amdgcn_global_load_lds((const unsigned*)((const char*)(gbase) + (voff)[_i]), (LAS unsigned*)(lds + (bufoff) + ldsw + _i * 8192), 16, 0, 0); } while (0)
; #define PG8_LDA(dst, b, h) do { _Pragma("unroll") for (int m = 0; m < 4; ++m) _Pragma("unroll") for (int k = 0; k < 2; ++k) dst[m][k] = *(const LAS bf16x8*)(lds + PG8_SA(b, h) + aoff + m * 2048 + k * 1024); } while (0)
; #define PG8_WAIT_V(n) asm volatile("s_waitcnt vmcnt(" #n ")" ::: "memory")
; template <class Epi>
; __device__ __forceinline__ void gemm_phase(int wv, LAS unsigned char* lds, const Gemm g, const StaticOrder& S, const Epi& E) {
;     ...
;     f32x4 acc[2][2][4][2];
; #pragma unroll
;     for (int a = 0; a < 2; ++a)
; #pragma unroll
;         for (int b = 0; b < 2; ++b)
; #pragma unroll
;             for (int m = 0; m < 4; ++m)
; #pragma unroll
;                 for (int n = 0; n < 2; ++n) acc[a][b][m][n] = (f32x4){0.f, 0.f, 0.f, 0.f};
;     bf16x8 At[4][2], B0[2][2], B1[2][2];
;     const char* cA = (const char*)g.A + (size_t)cur.pm * tstepA; const char* cB = (const char*)g.Bt + (size_t)cur.pn * tstepB;
;     PG8_STAGE(PG8_SB(0, 0), cB, voffB); PG8_STAGE(PG8_SA(0, 0), cA, voffA); PG8_STAGE(PG8_SB(0, 1), cB + hstepB, voffB); PG8_STAGE(PG8_SA(0, 1), cA + hstepA, voffA);
;     if (wr == 1) PG8_BAR;
;     PG8_WAIT_V(4); PG8_BAR;
;     PG8_STAGE(PG8_SB(1, 0), cB + kstep, voffB); PG8_STAGE(PG8_SA(1, 0), cA + kstep, voffA); PG8_STAGE(PG8_SB(1, 1), cB + hstepB + kstep, voffB);
;     PG8_WAIT_V(6); PG8_BAR;
;     for (;;) {
;         const bool has_next = S.next(ui + 1, nxt);
;         const char* nA = has_next ? (const char*)g.A + (size_t)nxt.pm * tstepA : cA; const char* nB = has_next ? (const char*)g.Bt + (size_t)nxt.pn * tstepB : cB;
;         for (int t = 0; t < nt; t += 2) {
;             const bool last = (t == nt - 2);
;             const char* a1 = cA + (size_t)(t + 1) * kstep;
;             const char* a2 = last ? nA : cA + (size_t)(t + 2) * kstep; const char* b2 = last ? nB : cB + (size_t)(t + 2) * kstep;
;             const char* a3 = a2 + kstep; const char* b3 = b2 + kstep;
;             PG8_LDB(B0, 0, 0); PG8_SCHED; PG8_LDA(At, 0, 0); PG8_STAGE(PG8_SA(1, 1), a1 + hstepA, voffA);
;             PG8_WAIT_L(8); PG8_BAR; PG8_WAIT_L(0); PG8_MMA(0, 0, At, B0); PG8_BAR; PG8_SCHED;
.LBB0_454:
	v_mov_b64_e32 v[2:3], 0xb00
	s_ashr_i32 s63, s62, 31
	v_cmp_lt_i64_e32 vcc, s[8:9], v[2:3]
	s_lshl_b64 s[8:9], s[62:63], 19
	v_readlane_b32 s10, v255, 19
	v_readlane_b32 s11, v255, 20
	s_add_u32 s86, s10, s8
	s_addc_u32 s87, s11, s9
	s_and_b64 s[8:9], vcc, exec
	s_cselect_b32 s10, s87, s5
	s_cselect_b32 s11, s86, s4
	s_ashr_i32 s53, s52, 31
	s_lshl_b64 s[8:9], s[52:53], 19
	s_add_u32 s94, s46, s8
	s_addc_u32 s95, s47, s9
	s_and_b64 s[8:9], vcc, exec
	s_cselect_b32 s13, s95, s7
	s_cselect_b32 s14, s94, s6
	s_add_u32 s4, s4, 0x40080
	s_addc_u32 s5, s5, 0
	s_add_u32 s15, s6, 0x100
	v_mov_b32_e32 v22, 0
	s_addc_u32 s16, s7, 0
	s_mov_b32 s17, -2
	v_mov_b32_e32 v23, v22
	v_mov_b32_e32 v24, v22
	v_mov_b32_e32 v25, v22
	v_mov_b32_e32 v90, v22
	v_mov_b32_e32 v91, v22
	v_mov_b32_e32 v92, v22
	v_mov_b32_e32 v93, v22
	v_mov_b32_e32 v18, v22
	v_mov_b32_e32 v19, v22
	v_mov_b32_e32 v20, v22
	v_mov_b32_e32 v21, v22
	v_mov_b32_e32 v82, v22
	v_mov_b32_e32 v83, v22
	v_mov_b32_e32 v84, v22
	v_mov_b32_e32 v85, v22
	v_mov_b32_e32 v26, v22
	v_mov_b32_e32 v27, v22
	v_mov_b32_e32 v28, v22
	v_mov_b32_e32 v29, v22
	v_mov_b32_e32 v86, v22
	v_mov_b32_e32 v87, v22
	v_mov_b32_e32 v88, v22
	v_mov_b32_e32 v89, v22
	v_mov_b32_e32 v30, v22
	v_mov_b32_e32 v31, v22
	v_mov_b32_e32 v32, v22
	v_mov_b32_e32 v33, v22
	v_mov_b32_e32 v94, v22
	v_mov_b32_e32 v95, v22
	v_mov_b32_e32 v96, v22
	v_mov_b32_e32 v97, v22
	v_mov_b32_e32 v10, v22
	v_mov_b32_e32 v11, v22
	v_mov_b32_e32 v12, v22
	v_mov_b32_e32 v13, v22
	v_mov_b32_e32 v74, v22
	v_mov_b32_e32 v75, v22
	v_mov_b32_e32 v76, v22
	v_mov_b32_e32 v77, v22
	v_mov_b32_e32 v2, v22
	v_mov_b32_e32 v3, v22
	v_mov_b32_e32 v4, v22
	v_mov_b32_e32 v5, v22
	v_mov_b32_e32 v66, v22
	v_mov_b32_e32 v67, v22
	v_mov_b32_e32 v68, v22
	v_mov_b32_e32 v69, v22
	v_mov_b32_e32 v6, v22
	v_mov_b32_e32 v7, v22
	v_mov_b32_e32 v8, v22
	v_mov_b32_e32 v9, v22
	v_mov_b32_e32 v70, v22
	v_mov_b32_e32 v71, v22
	v_mov_b32_e32 v72, v22
	v_mov_b32_e32 v73, v22
	v_mov_b32_e32 v14, v22
	v_mov_b32_e32 v15, v22
	v_mov_b32_e32 v16, v22
	v_mov_b32_e32 v17, v22
	v_mov_b32_e32 v78, v22
	v_mov_b32_e32 v79, v22
	v_mov_b32_e32 v80, v22
	v_mov_b32_e32 v81, v22
	v_mov_b32_e32 v58, v22
	v_mov_b32_e32 v59, v22
	v_mov_b32_e32 v60, v22
	v_mov_b32_e32 v61, v22
	v_mov_b32_e32 v158, v22
	v_mov_b32_e32 v159, v22
	v_mov_b32_e32 v160, v22
	v_mov_b32_e32 v161, v22
	v_mov_b32_e32 v50, v22
	v_mov_b32_e32 v51, v22
	v_mov_b32_e32 v52, v22
	v_mov_b32_e32 v53, v22
	v_mov_b32_e32 v150, v22
	v_mov_b32_e32 v151, v22
	v_mov_b32_e32 v152, v22
	v_mov_b32_e32 v153, v22
	v_mov_b32_e32 v54, v22
	v_mov_b32_e32 v55, v22
	v_mov_b32_e32 v56, v22
	v_mov_b32_e32 v57, v22
	v_mov_b32_e32 v154, v22
	v_mov_b32_e32 v155, v22
	v_mov_b32_e32 v156, v22
	v_mov_b32_e32 v157, v22
	v_mov_b32_e32 v62, v22
	v_mov_b32_e32 v63, v22
	v_mov_b32_e32 v64, v22
	v_mov_b32_e32 v65, v22
	v_mov_b32_e32 v166, v22
	v_mov_b32_e32 v167, v22
	v_mov_b32_e32 v168, v22
	v_mov_b32_e32 v169, v22
	v_mov_b32_e32 v42, v22
	v_mov_b32_e32 v43, v22
	v_mov_b32_e32 v44, v22
	v_mov_b32_e32 v45, v22
	v_mov_b32_e32 v142, v22
	v_mov_b32_e32 v143, v22
	v_mov_b32_e32 v144, v22
	v_mov_b32_e32 v145, v22
	v_mov_b32_e32 v34, v22
	v_mov_b32_e32 v35, v22
	v_mov_b32_e32 v36, v22
	v_mov_b32_e32 v37, v22
	v_mov_b32_e32 v130, v22
	v_mov_b32_e32 v131, v22
	v_mov_b32_e32 v132, v22
	v_mov_b32_e32 v133, v22
	v_mov_b32_e32 v38, v22
	v_mov_b32_e32 v39, v22
	v_mov_b32_e32 v40, v22
	v_mov_b32_e32 v41, v22
	v_mov_b32_e32 v134, v22
	v_mov_b32_e32 v135, v22
	v_mov_b32_e32 v136, v22
	v_mov_b32_e32 v137, v22
	v_mov_b32_e32 v46, v22
	v_mov_b32_e32 v47, v22
	v_mov_b32_e32 v48, v22
	v_mov_b32_e32 v49, v22
	v_mov_b32_e32 v146, v22
	v_mov_b32_e32 v147, v22
	v_mov_b32_e32 v148, v22
	v_mov_b32_e32 v149, v22
	v_add_u32_e32 v110, 0x10000, v1
	ds_read_b128 v[98:101], v110
	ds_read_b128 v[102:105], v110 offset:1024
	ds_read_b128 v[106:109], v110 offset:2048
	ds_read_b128 v[110:113], v110 offset:3072
.LBB0_455:
	s_add_u32 s6, s4, 0xfffc0080
	s_addc_u32 s7, s5, -1
	s_add_i32 s42, 0, 0x10000
	s_cmp_eq_u32 s17, 12
	s_cselect_b32 s9, s10, s7
	s_cselect_b32 s8, s11, s6
	s_cselect_b32 s7, s13, s16
	s_cselect_b32 s6, s14, s15
	v_lshl_add_u64 v[192:193], s[4:5], 0, v[180:181]
	s_add_i32 m0, s60, 0xc000
	ds_read_b128 v[114:117], v179
	ds_read_b128 v[118:121], v179 offset:1024
	ds_read_b128 v[122:125], v179 offset:2048
	ds_read_b128 v[126:129], v179 offset:3072
	ds_read_b128 v[138:141], v179 offset:4096
	ds_read_b128 v[162:165], v179 offset:5120
	ds_read_b128 v[184:187], v179 offset:6144
	ds_read_b128 v[188:191], v179 offset:7168
	global_load_lds_dwordx4 v[192:193], off
	v_lshl_add_u64 v[192:193], s[4:5], 0, v[182:183]
	s_add_i32 m0, s60, 0xe000
	s_nop 0
	global_load_lds_dwordx4 v[192:193], off
	s_waitcnt lgkmcnt(8)
	s_barrier
	s_waitcnt lgkmcnt(0)
	s_setprio 1
	s_waitcnt lgkmcnt(0)
	v_mfma_f32_16x16x32_bf16 v[146:149], v[98:101], v[114:117], v[146:149]
	v_mfma_f32_16x16x32_bf16 v[46:49], v[106:109], v[114:117], v[46:49]
	v_mfma_f32_16x16x32_bf16 v[134:137], v[98:101], v[122:125], v[134:137]
	v_mfma_f32_16x16x32_bf16 v[38:41], v[106:109], v[122:125], v[38:41]
	v_mfma_f32_16x16x32_bf16 v[130:133], v[98:101], v[138:141], v[130:133]
	v_mfma_f32_16x16x32_bf16 v[34:37], v[106:109], v[138:141], v[34:37]
	v_mfma_f32_16x16x32_bf16 v[142:145], v[98:101], v[184:187], v[142:145]
	v_mfma_f32_16x16x32_bf16 v[42:45], v[106:109], v[184:187], v[42:45]
	v_mfma_f32_16x16x32_bf16 v[146:149], v[102:105], v[118:121], v[146:149]
	v_mfma_f32_16x16x32_bf16 v[46:49], v[110:113], v[118:121], v[46:49]
	v_mfma_f32_16x16x32_bf16 v[134:137], v[102:105], v[126:129], v[134:137]
	v_mfma_f32_16x16x32_bf16 v[38:41], v[110:113], v[126:129], v[38:41]
	v_mfma_f32_16x16x32_bf16 v[130:133], v[102:105], v[162:165], v[130:133]
	v_mfma_f32_16x16x32_bf16 v[34:37], v[110:113], v[162:165], v[34:37]
	v_mfma_f32_16x16x32_bf16 v[142:145], v[102:105], v[188:191], v[142:145]
	v_mfma_f32_16x16x32_bf16 v[42:45], v[110:113], v[188:191], v[42:45]
	s_setprio 0
	s_barrier
; #define PG8_STAGE(bufoff, gbase, voff) do { _Pragma("unroll") for (int _i = 0; _i < 2; ++_i) \
;         __builtin_amdgcn_global_load_lds((const unsigned*)((const char*)(gbase) + (voff)[_i]), (LAS unsigned*)(lds + (bufoff) + ldsw + _i * 8192), 16, 0, 0); } while (0)
; #define PG8_LDA(dst, b, h) do { _Pragma("unroll") for (int m = 0; m < 4; ++m) _Pragma("unroll") for (int k = 0; k < 2; ++k) dst[m][k] = *(const LAS bf16x8*)(lds + PG8_SA(b, h) + aoff + m * 2048 + k * 1024); } while (0)
; #define PG8_LDB(dst, b, h) do { _Pragma("unroll") for (int n = 0; n < 2; ++n) _Pragma("unroll") for (int k = 0; k < 2; ++k) dst[n][k] = *(const LAS bf16x8*)(lds + PG8_SB(b, h) + boff + n * 2048 + k * 1024); } while (0)
; #define PG8_MMA(ai, bj, At, Bt) do { __builtin_amdgcn_s_setprio(1); _Pragma("unroll") for (int m = 0; m < 4; ++m) _Pragma("unroll") for (int n = 0; n < 2; ++n) _Pragma("unroll") for (int k = 0; k < 2; ++k) \
;         acc[ai][bj][m][n] = __builtin_amdgcn_mfma_f32_16x16x32_bf16(Bt[n][k], At[m][k], acc[ai][bj][m][n], 0, 0, 0); __builtin_amdgcn_s_setprio(0); } while (0)
; #define PG8_WAIT_V(n) asm volatile("s_waitcnt vmcnt(" #n ")" ::: "memory")
; #define PG8_WAIT_L(n) asm volatile("s_waitcnt lgkmcnt(" #n ")" ::: "memory")
; #define PG8_BAR __builtin_amdgcn_s_barrier()
; #define PG8_SCHED __builtin_amdgcn_sched_barrier(0)
; template <class Epi>
; __device__ __forceinline__ void gemm_phase(int wv, LAS unsigned char* lds, const Gemm g, const StaticOrder& S, const Epi& E) {
;     ...
;             PG8_LDB(B1, 0, 1); PG8_STAGE(PG8_SB(0, 0), b2, voffB);
;             PG8_BAR; PG8_WAIT_L(0); PG8_MMA(0, 1, At, B1); PG8_BAR;
;             PG8_LDA(At, 0, 1); PG8_STAGE(PG8_SA(0, 0), a2, voffA);
;             PG8_BAR; PG8_WAIT_L(0); PG8_MMA(1, 0, At, B0); PG8_BAR; PG8_SCHED;
;             PG8_STAGE(PG8_SB(0, 1), b2 + hstepB, voffB);
;             PG8_WAIT_V(6); PG8_BAR; PG8_MMA(1, 1, At, B1); PG8_BAR;
;             PG8_LDB(B0, 1, 0); PG8_SCHED; PG8_LDA(At, 1, 0); PG8_STAGE(PG8_SA(0, 1), a2 + hstepA, voffA);
	s_add_i32 s44, 0, 0x14000
	s_add_i32 s42, s42, s59
	v_add_u32_e32 v204, s44, v1
	v_lshl_add_u64 v[212:213], s[6:7], 0, v[174:175]
	s_mov_b32 m0, s42
	ds_read_b128 v[192:195], v204
	ds_read_b128 v[196:199], v204 offset:1024
	ds_read_b128 v[200:203], v204 offset:2048
	ds_read_b128 v[204:207], v204 offset:3072
	global_load_lds_dwordx4 v[212:213], off
	v_lshl_add_u64 v[214:215], s[6:7], 0, v[170:171]
	s_add_i32 m0, s42, 0x2000
	s_nop 0
	global_load_lds_dwordx4 v[214:215], off
	s_barrier
	s_waitcnt lgkmcnt(0)
	s_setprio 1
	s_waitcnt lgkmcnt(0)
	v_mfma_f32_16x16x32_bf16 v[166:169], v[192:195], v[114:117], v[166:169]
	v_mfma_f32_16x16x32_bf16 v[62:65], v[200:203], v[114:117], v[62:65]
	v_mfma_f32_16x16x32_bf16 v[54:57], v[200:203], v[122:125], v[54:57]
	v_mfma_f32_16x16x32_bf16 v[50:53], v[200:203], v[138:141], v[50:53]
	v_mfma_f32_16x16x32_bf16 v[58:61], v[200:203], v[184:187], v[58:61]
	v_mfma_f32_16x16x32_bf16 v[166:169], v[196:199], v[118:121], v[166:169]
	v_mfma_f32_16x16x32_bf16 v[62:65], v[204:207], v[118:121], v[62:65]
	v_mfma_f32_16x16x32_bf16 v[114:117], v[192:195], v[122:125], v[154:157]
	v_mfma_f32_16x16x32_bf16 v[54:57], v[204:207], v[126:129], v[54:57]
	v_mfma_f32_16x16x32_bf16 v[118:121], v[192:195], v[138:141], v[150:153]
	v_mfma_f32_16x16x32_bf16 v[50:53], v[204:207], v[162:165], v[50:53]
	v_mfma_f32_16x16x32_bf16 v[122:125], v[192:195], v[184:187], v[158:161]
	v_mfma_f32_16x16x32_bf16 v[58:61], v[204:207], v[188:191], v[58:61]
	v_mfma_f32_16x16x32_bf16 v[114:117], v[196:199], v[126:129], v[114:117]
	v_mfma_f32_16x16x32_bf16 v[118:121], v[196:199], v[162:165], v[118:121]
	v_mfma_f32_16x16x32_bf16 v[122:125], v[196:199], v[188:191], v[122:125]
	s_setprio 0
	s_mov_b32 m0, s60
	v_lshl_add_u64 v[216:217], s[8:9], 0, v[176:177]
	s_barrier
	ds_read_b128 v[126:129], v179 offset:16384
	ds_read_b128 v[138:141], v179 offset:17408
	ds_read_b128 v[150:153], v179 offset:18432
	ds_read_b128 v[154:157], v179 offset:19456
	ds_read_b128 v[158:161], v179 offset:20480
	ds_read_b128 v[162:165], v179 offset:21504
	ds_read_b128 v[184:187], v179 offset:22528
	ds_read_b128 v[188:191], v179 offset:23552
	global_load_lds_dwordx4 v[216:217], off
	v_lshl_add_u64 v[218:219], s[8:9], 0, v[172:173]
	s_mov_b32 m0, s61
	s_nop 0
	global_load_lds_dwordx4 v[218:219], off
	s_barrier
	s_waitcnt lgkmcnt(0)
	s_setprio 1
	s_waitcnt lgkmcnt(0)
	v_mfma_f32_16x16x32_bf16 v[78:81], v[98:101], v[126:129], v[78:81]
	v_mfma_f32_16x16x32_bf16 v[14:17], v[106:109], v[126:129], v[14:17]
	v_mfma_f32_16x16x32_bf16 v[70:73], v[98:101], v[150:153], v[70:73]
	v_mfma_f32_16x16x32_bf16 v[6:9], v[106:109], v[150:153], v[6:9]
	v_mfma_f32_16x16x32_bf16 v[66:69], v[98:101], v[158:161], v[66:69]
	v_mfma_f32_16x16x32_bf16 v[2:5], v[106:109], v[158:161], v[2:5]
	v_mfma_f32_16x16x32_bf16 v[74:77], v[98:101], v[184:187], v[74:77]
	v_mfma_f32_16x16x32_bf16 v[10:13], v[106:109], v[184:187], v[10:13]
	v_mfma_f32_16x16x32_bf16 v[78:81], v[102:105], v[138:141], v[78:81]
	v_mfma_f32_16x16x32_bf16 v[14:17], v[110:113], v[138:141], v[14:17]
	v_mfma_f32_16x16x32_bf16 v[70:73], v[102:105], v[154:157], v[70:73]
	v_mfma_f32_16x16x32_bf16 v[6:9], v[110:113], v[154:157], v[6:9]
	v_mfma_f32_16x16x32_bf16 v[66:69], v[102:105], v[162:165], v[66:69]
	v_mfma_f32_16x16x32_bf16 v[2:5], v[110:113], v[162:165], v[2:5]
	v_mfma_f32_16x16x32_bf16 v[74:77], v[102:105], v[188:191], v[74:77]
	v_mfma_f32_16x16x32_bf16 v[10:13], v[110:113], v[188:191], v[10:13]
	s_setprio 0
	s_barrier
	s_add_u32 s54, s6, 0x40000
	s_addc_u32 s55, s7, 0
	s_add_i32 s42, s44, s59
	v_lshl_add_u64 v[98:99], s[54:55], 0, v[174:175]
	s_mov_b32 m0, s42
	s_nop 0
	global_load_lds_dwordx4 v[98:99], off
	v_lshl_add_u64 v[98:99], s[54:55], 0, v[170:171]
	s_add_i32 m0, s42, 0x2000
	s_nop 0
	global_load_lds_dwordx4 v[98:99], off
	s_waitcnt vmcnt(6)
	s_barrier
	s_setprio 1
	v_add_u32_e32 v110, 0x18000, v1
	ds_read_b128 v[98:101], v110
	ds_read_b128 v[102:105], v110 offset:1024
	ds_read_b128 v[106:109], v110 offset:2048
	ds_read_b128 v[110:113], v110 offset:3072
	v_mfma_f32_16x16x32_bf16 v[94:97], v[192:195], v[126:129], v[94:97]
	v_mfma_f32_16x16x32_bf16 v[30:33], v[200:203], v[126:129], v[30:33]
	v_mfma_f32_16x16x32_bf16 v[86:89], v[192:195], v[150:153], v[86:89]
	v_mfma_f32_16x16x32_bf16 v[26:29], v[200:203], v[150:153], v[26:29]
	v_mfma_f32_16x16x32_bf16 v[82:85], v[192:195], v[158:161], v[82:85]
	v_mfma_f32_16x16x32_bf16 v[18:21], v[200:203], v[158:161], v[18:21]
	v_mfma_f32_16x16x32_bf16 v[90:93], v[192:195], v[184:187], v[90:93]
	v_mfma_f32_16x16x32_bf16 v[22:25], v[200:203], v[184:187], v[22:25]
	v_mfma_f32_16x16x32_bf16 v[94:97], v[196:199], v[138:141], v[94:97]
	v_mfma_f32_16x16x32_bf16 v[30:33], v[204:207], v[138:141], v[30:33]
	v_mfma_f32_16x16x32_bf16 v[86:89], v[196:199], v[154:157], v[86:89]
	v_mfma_f32_16x16x32_bf16 v[26:29], v[204:207], v[154:157], v[26:29]
	v_mfma_f32_16x16x32_bf16 v[82:85], v[196:199], v[162:165], v[82:85]
	v_mfma_f32_16x16x32_bf16 v[18:21], v[204:207], v[162:165], v[18:21]
	v_mfma_f32_16x16x32_bf16 v[90:93], v[196:199], v[188:191], v[90:93]
	v_mfma_f32_16x16x32_bf16 v[22:25], v[204:207], v[188:191], v[22:25]
	s_setprio 0
	s_add_i32 s42, 0, 0x18000
	s_barrier
	s_add_u32 s8, s8, 0x40000
	s_addc_u32 s9, s9, 0
	s_mov_b32 m0, s64
	v_lshl_add_u64 v[154:155], s[8:9], 0, v[176:177]
	ds_read_b128 v[126:129], v179 offset:32768
	ds_read_b128 v[138:141], v179 offset:33792
	ds_read_b128 v[150:153], v179 offset:34816
	ds_read_b128 v[158:161], v179 offset:35840
	ds_read_b128 v[162:165], v179 offset:36864
	ds_read_b128 v[184:187], v179 offset:37888
	ds_read_b128 v[188:191], v179 offset:38912
	ds_read_b128 v[192:195], v179 offset:39936
	global_load_lds_dwordx4 v[154:155], off
	v_lshl_add_u64 v[154:155], s[8:9], 0, v[172:173]
	s_mov_b32 m0, s65
	s_nop 0
	global_load_lds_dwordx4 v[154:155], off
	s_waitcnt lgkmcnt(8)
	s_barrier
; #define PG8_STAGE(bufoff, gbase, voff) do { _Pragma("unroll") for (int _i = 0; _i < 2; ++_i) \
;         __builtin_amdgcn_global_load_lds((const unsigned*)((const char*)(gbase) + (voff)[_i]), (LAS unsigned*)(lds + (bufoff) + ldsw + _i * 8192), 16, 0, 0); } while (0)
; #define PG8_LDA(dst, b, h) do { _Pragma("unroll") for (int m = 0; m < 4; ++m) _Pragma("unroll") for (int k = 0; k < 2; ++k) dst[m][k] = *(const LAS bf16x8*)(lds + PG8_SA(b, h) + aoff + m * 2048 + k * 1024); } while (0)
; #define PG8_LDB(dst, b, h) do { _Pragma("unroll") for (int n = 0; n < 2; ++n) _Pragma("unroll") for (int k = 0; k < 2; ++k) dst[n][k] = *(const LAS bf16x8*)(lds + PG8_SB(b, h) + boff + n * 2048 + k * 1024); } while (0)
; #define PG8_MMA(ai, bj, At, Bt) do { __builtin_amdgcn_s_setprio(1); _Pragma("unroll") for (int m = 0; m < 4; ++m) _Pragma("unroll") for (int n = 0; n < 2; ++n) _Pragma("unroll") for (int k = 0; k < 2; ++k) \
;         acc[ai][bj][m][n] = __builtin_amdgcn_mfma_f32_16x16x32_bf16(Bt[n][k], At[m][k], acc[ai][bj][m][n], 0, 0, 0); __builtin_amdgcn_s_setprio(0); } while (0)
; #define PG8_WAIT_V(n) asm volatile("s_waitcnt vmcnt(" #n ")" ::: "memory")
; #define PG8_WAIT_L(n) asm volatile("s_waitcnt lgkmcnt(" #n ")" ::: "memory")
; #define PG8_BAR __builtin_amdgcn_s_barrier()
; #define PG8_SCHED __builtin_amdgcn_sched_barrier(0)
; template <class Epi>
; __device__ __forceinline__ void gemm_phase(int wv, LAS unsigned char* lds, const Gemm g, const StaticOrder& S, const Epi& E) {
;     ...
;             PG8_WAIT_L(8); PG8_BAR; PG8_WAIT_L(0); PG8_MMA(0, 0, At, B0); PG8_BAR; PG8_SCHED;
;             PG8_LDB(B1, 1, 1); PG8_STAGE(PG8_SB(1, 0), b3, voffB);
;             PG8_BAR; PG8_WAIT_L(0); PG8_MMA(0, 1, At, B1); PG8_BAR;
;             PG8_LDA(At, 1, 1); PG8_STAGE(PG8_SA(1, 0), a3, voffA);
;             PG8_BAR; PG8_WAIT_L(0); PG8_MMA(1, 0, At, B0); PG8_BAR; PG8_SCHED;
;             PG8_STAGE(PG8_SB(1, 1), b3 + hstepB, voffB);
;             PG8_WAIT_V(6); PG8_BAR; PG8_MMA(1, 1, At, B1); PG8_BAR;
	s_waitcnt lgkmcnt(0)
	s_setprio 1
	s_waitcnt lgkmcnt(0)
	v_mfma_f32_16x16x32_bf16 v[146:149], v[98:101], v[126:129], v[146:149]
	v_mfma_f32_16x16x32_bf16 v[46:49], v[106:109], v[126:129], v[46:49]
	v_mfma_f32_16x16x32_bf16 v[134:137], v[98:101], v[150:153], v[134:137]
	v_mfma_f32_16x16x32_bf16 v[38:41], v[106:109], v[150:153], v[38:41]
	v_mfma_f32_16x16x32_bf16 v[130:133], v[98:101], v[162:165], v[130:133]
	v_mfma_f32_16x16x32_bf16 v[34:37], v[106:109], v[162:165], v[34:37]
	v_mfma_f32_16x16x32_bf16 v[142:145], v[98:101], v[188:191], v[142:145]
	v_mfma_f32_16x16x32_bf16 v[42:45], v[106:109], v[188:191], v[42:45]
	v_mfma_f32_16x16x32_bf16 v[146:149], v[102:105], v[138:141], v[146:149]
	v_mfma_f32_16x16x32_bf16 v[46:49], v[110:113], v[138:141], v[46:49]
	v_mfma_f32_16x16x32_bf16 v[134:137], v[102:105], v[158:161], v[134:137]
	v_mfma_f32_16x16x32_bf16 v[38:41], v[110:113], v[158:161], v[38:41]
	v_mfma_f32_16x16x32_bf16 v[130:133], v[102:105], v[184:187], v[130:133]
	v_mfma_f32_16x16x32_bf16 v[34:37], v[110:113], v[184:187], v[34:37]
	v_mfma_f32_16x16x32_bf16 v[142:145], v[102:105], v[192:195], v[142:145]
	v_mfma_f32_16x16x32_bf16 v[42:45], v[110:113], v[192:195], v[42:45]
	s_setprio 0
	s_barrier
	s_add_i32 s8, 0, 0x1c000
	v_add_u32_e32 v154, s8, v1
	s_add_i32 s9, s42, s59
	ds_read_b128 v[196:199], v154
	ds_read_b128 v[200:203], v154 offset:1024
	ds_read_b128 v[204:207], v154 offset:2048
	ds_read_b128 v[208:211], v154 offset:3072
	v_lshl_add_u64 v[154:155], v[212:213], 0, s[38:39]
	s_mov_b32 m0, s9
	s_nop 0
	global_load_lds_dwordx4 v[154:155], off
	v_lshl_add_u64 v[154:155], v[214:215], 0, s[38:39]
	s_add_i32 m0, s9, 0x2000
	s_nop 0
	global_load_lds_dwordx4 v[154:155], off
	s_barrier
	s_waitcnt lgkmcnt(0)
	s_setprio 1
	s_waitcnt lgkmcnt(0)
	v_mfma_f32_16x16x32_bf16 v[154:157], v[196:199], v[126:129], v[166:169]
	v_mfma_f32_16x16x32_bf16 v[114:117], v[196:199], v[150:153], v[114:117]
	v_mfma_f32_16x16x32_bf16 v[166:169], v[200:203], v[138:141], v[154:157]
	v_mfma_f32_16x16x32_bf16 v[154:157], v[200:203], v[158:161], v[114:117]
	v_mfma_f32_16x16x32_bf16 v[114:117], v[196:199], v[162:165], v[118:121]
	v_mfma_f32_16x16x32_bf16 v[62:65], v[204:207], v[126:129], v[62:65]
	v_mfma_f32_16x16x32_bf16 v[54:57], v[204:207], v[150:153], v[54:57]
	v_mfma_f32_16x16x32_bf16 v[150:153], v[200:203], v[184:187], v[114:117]
	v_mfma_f32_16x16x32_bf16 v[50:53], v[204:207], v[162:165], v[50:53]
	v_mfma_f32_16x16x32_bf16 v[114:117], v[196:199], v[188:191], v[122:125]
	v_mfma_f32_16x16x32_bf16 v[58:61], v[204:207], v[188:191], v[58:61]
	v_mfma_f32_16x16x32_bf16 v[62:65], v[208:211], v[138:141], v[62:65]
	v_mfma_f32_16x16x32_bf16 v[54:57], v[208:211], v[158:161], v[54:57]
	v_mfma_f32_16x16x32_bf16 v[50:53], v[208:211], v[184:187], v[50:53]
	v_mfma_f32_16x16x32_bf16 v[158:161], v[200:203], v[192:195], v[114:117]
	v_mfma_f32_16x16x32_bf16 v[58:61], v[208:211], v[192:195], v[58:61]
	s_setprio 0
	s_mov_b32 m0, s71
	v_lshl_add_u64 v[192:193], v[216:217], 0, s[38:39]
	s_barrier
	ds_read_b128 v[114:117], v179 offset:49152
	ds_read_b128 v[118:121], v179 offset:50176
	ds_read_b128 v[122:125], v179 offset:51200
	ds_read_b128 v[126:129], v179 offset:52224
	ds_read_b128 v[138:141], v179 offset:53248
	ds_read_b128 v[162:165], v179 offset:54272
	ds_read_b128 v[184:187], v179 offset:55296
	ds_read_b128 v[188:191], v179 offset:56320
	global_load_lds_dwordx4 v[192:193], off
	v_lshl_add_u64 v[192:193], v[218:219], 0, s[38:39]
	s_mov_b32 m0, s72
	s_nop 0
	global_load_lds_dwordx4 v[192:193], off
	s_barrier
	s_waitcnt lgkmcnt(0)
	s_setprio 1
	s_waitcnt lgkmcnt(0)
	v_mfma_f32_16x16x32_bf16 v[78:81], v[98:101], v[114:117], v[78:81]
	v_mfma_f32_16x16x32_bf16 v[14:17], v[106:109], v[114:117], v[14:17]
	v_mfma_f32_16x16x32_bf16 v[70:73], v[98:101], v[122:125], v[70:73]
	v_mfma_f32_16x16x32_bf16 v[6:9], v[106:109], v[122:125], v[6:9]
	v_mfma_f32_16x16x32_bf16 v[66:69], v[98:101], v[138:141], v[66:69]
	v_mfma_f32_16x16x32_bf16 v[2:5], v[106:109], v[138:141], v[2:5]
	v_mfma_f32_16x16x32_bf16 v[74:77], v[98:101], v[184:187], v[74:77]
	v_mfma_f32_16x16x32_bf16 v[10:13], v[106:109], v[184:187], v[10:13]
	v_mfma_f32_16x16x32_bf16 v[78:81], v[102:105], v[118:121], v[78:81]
	v_mfma_f32_16x16x32_bf16 v[14:17], v[110:113], v[118:121], v[14:17]
	v_mfma_f32_16x16x32_bf16 v[70:73], v[102:105], v[126:129], v[70:73]
	v_mfma_f32_16x16x32_bf16 v[6:9], v[110:113], v[126:129], v[6:9]
	v_mfma_f32_16x16x32_bf16 v[66:69], v[102:105], v[162:165], v[66:69]
	v_mfma_f32_16x16x32_bf16 v[2:5], v[110:113], v[162:165], v[2:5]
	v_mfma_f32_16x16x32_bf16 v[74:77], v[102:105], v[188:191], v[74:77]
	v_mfma_f32_16x16x32_bf16 v[10:13], v[110:113], v[188:191], v[10:13]
	s_setprio 0
	s_barrier
	s_add_u32 s6, s6, 0x40080
	s_addc_u32 s7, s7, 0
	s_add_i32 s8, s8, s59
	v_lshl_add_u64 v[98:99], s[6:7], 0, v[174:175]
	s_mov_b32 m0, s8
	s_nop 0
	global_load_lds_dwordx4 v[98:99], off
	v_lshl_add_u64 v[98:99], s[6:7], 0, v[170:171]
	s_add_i32 m0, s8, 0x2000
	s_nop 0
	global_load_lds_dwordx4 v[98:99], off
	s_waitcnt vmcnt(6)
	s_barrier
; template <class Epi>
; __device__ __forceinline__ void gemm_phase(int wv, LAS unsigned char* lds, const Gemm g, const StaticOrder& S, const Epi& E) {
;     ...
;             PG8_LDB(B0, 0, 0); PG8_SCHED; PG8_LDA(At, 0, 0); PG8_STAGE(PG8_SA(1, 1), a1 + hstepA, voffA);
;             PG8_WAIT_L(8); PG8_BAR; PG8_WAIT_L(0); PG8_MMA(0, 0, At, B0); PG8_BAR; PG8_SCHED;
;             PG8_LDB(B1, 0, 1); PG8_STAGE(PG8_SB(0, 0), b2, voffB);
;             PG8_BAR; PG8_WAIT_L(0); PG8_MMA(0, 1, At, B1); PG8_BAR;
;             PG8_LDA(At, 0, 1); PG8_STAGE(PG8_SA(0, 0), a2, voffA);
;             PG8_BAR; PG8_WAIT_L(0); PG8_MMA(1, 0, At, B0); PG8_BAR; PG8_SCHED;
;             PG8_STAGE(PG8_SB(0, 1), b2 + hstepB, voffB);
;             PG8_WAIT_V(6); PG8_BAR; PG8_MMA(1, 1, At, B1); PG8_BAR;
;             PG8_LDB(B0, 1, 0); PG8_SCHED; PG8_LDA(At, 1, 0); PG8_STAGE(PG8_SA(0, 1), a2 + hstepA, voffA);
;             PG8_WAIT_L(8); PG8_BAR; PG8_WAIT_L(0); PG8_MMA(0, 0, At, B0); PG8_BAR; PG8_SCHED;
;             PG8_LDB(B1, 1, 1); PG8_STAGE(PG8_SB(1, 0), b3, voffB);
;             PG8_BAR; PG8_WAIT_L(0); PG8_MMA(0, 1, At, B1); PG8_BAR;
;             PG8_LDA(At, 1, 1); PG8_STAGE(PG8_SA(1, 0), a3, voffA);
;             PG8_BAR; PG8_WAIT_L(0); PG8_MMA(1, 0, At, B0); PG8_BAR; PG8_SCHED;
;             PG8_STAGE(PG8_SB(1, 1), b3 + hstepB, voffB);
;             PG8_WAIT_V(6); PG8_BAR; PG8_MMA(1, 1, At, B1); PG8_BAR;
;     __device__ __forceinline__ void operator()(const f32x4 (&acc)[2][2][4][2], const Unit& u, int wr, int wc, int fr, int fq) const {
;         asm volatile("" : "+v"(fr), "+v"(fq));
;         const int row0 = u.pm * BM + wr * 64 + fr, colt = u.pn * BM + wc * 32 + 8 * fq;
;         const int seq = seq_of_row(u.pm * BM);
;         const float* biasp = bias + (size_t)seq * NUP + colt; const float* cwp = cw + colt;
;         float rs[2][4];
; #pragma unroll
;         for (int ai = 0; ai < 2; ++ai)
; #pragma unroll
;             for (int m = 0; m < 4; ++m) rs[ai][m] = (float)ssin[row0 + ai * HALF + m * 16];
; #pragma unroll
;         for (int ai = 0; ai < 2; ++ai)
; #pragma unroll
;             for (int m = 0; m < 4; ++m) rs[ai][m] = __builtin_amdgcn_rsqf(rs[ai][m] * SSKI + EPSN);
; #pragma unroll
;         for (int n = 0; n < 2; ++n) {
;             f32x4 prm[2][5];
; #pragma unroll
;             for (int bj = 0; bj < 2; ++bj) { const int co = bj * HALF + 4 * n;
	s_setprio 1
	v_add_u32_e32 v110, 0x10000, v1
	ds_read_b128 v[98:101], v110
	ds_read_b128 v[102:105], v110 offset:1024
	ds_read_b128 v[106:109], v110 offset:2048
	ds_read_b128 v[110:113], v110 offset:3072
	v_mfma_f32_16x16x32_bf16 v[94:97], v[196:199], v[114:117], v[94:97]
	v_mfma_f32_16x16x32_bf16 v[30:33], v[204:207], v[114:117], v[30:33]
	v_mfma_f32_16x16x32_bf16 v[86:89], v[196:199], v[122:125], v[86:89]
	v_mfma_f32_16x16x32_bf16 v[26:29], v[204:207], v[122:125], v[26:29]
	v_mfma_f32_16x16x32_bf16 v[82:85], v[196:199], v[138:141], v[82:85]
	v_mfma_f32_16x16x32_bf16 v[18:21], v[204:207], v[138:141], v[18:21]
	v_mfma_f32_16x16x32_bf16 v[90:93], v[196:199], v[184:187], v[90:93]
	v_mfma_f32_16x16x32_bf16 v[22:25], v[204:207], v[184:187], v[22:25]
	v_mfma_f32_16x16x32_bf16 v[94:97], v[200:203], v[118:121], v[94:97]
	v_mfma_f32_16x16x32_bf16 v[30:33], v[208:211], v[118:121], v[30:33]
	v_mfma_f32_16x16x32_bf16 v[86:89], v[200:203], v[126:129], v[86:89]
	v_mfma_f32_16x16x32_bf16 v[26:29], v[208:211], v[126:129], v[26:29]
	v_mfma_f32_16x16x32_bf16 v[82:85], v[200:203], v[162:165], v[82:85]
	v_mfma_f32_16x16x32_bf16 v[18:21], v[208:211], v[162:165], v[18:21]
	v_mfma_f32_16x16x32_bf16 v[90:93], v[200:203], v[188:191], v[90:93]
	v_mfma_f32_16x16x32_bf16 v[22:25], v[208:211], v[188:191], v[22:25]
	s_setprio 0
	s_add_i32 s17, s17, 2
	s_add_u32 s4, s4, 0x100
	s_addc_u32 s5, s5, 0
	s_add_u32 s15, s15, 0x100
	s_addc_u32 s16, s16, 0
	s_cmp_gt_u32 s17, 13
	s_barrier
	s_cbranch_scc0 .LBB0_455
	s_waitcnt lgkmcnt(0)
	v_mbcnt_lo_u32_b32 v246, -1, 0
	v_mbcnt_hi_u32_b32 v246, -1, v246
	s_lshl_b32 s4, s12, 8
	s_add_i32 s5, s4, s67
	v_and_b32_e32 v247, 15, v246
	v_bfe_u32 v248, v246, 4, 2
	s_cmpk_lt_u32 s4, 0x4000
	s_movk_i32 s7, 0x2c00
	s_cselect_b32 s7, 0x1600, s7
	s_cmp_gt_i32 s12, 31
	s_cselect_b32 s7, s7, 0
	s_lshl_b32 s7, s7, 2
	s_add_u32 s8, s48, s7
	s_addc_u32 s9, s49, 0
	s_add_u32 s10, s68, 0x5800
	s_addc_u32 s11, s69, 0
	s_add_u32 s14, s68, 0x10800
	s_addc_u32 s15, s69, 0
	v_lshl_add_u32 v249, v247, 2, s5
	v_lshlrev_b32_e32 v249, 3, v249
	s_lshl_b32 s6, s36, 8
	s_or_b32 s6, s6, s70
	v_lshl_add_u32 v244, v248, 3, s6
	v_lshlrev_b32_e32 v244, 2, v244
	global_load_dwordx4 v[184:187], v249, s[22:23]
	global_load_dwordx4 v[188:191], v249, s[22:23] offset:16
	global_load_dwordx4 v[192:195], v249, s[22:23] offset:1024
	global_load_dwordx4 v[196:199], v249, s[22:23] offset:1040
	s_lshl_b32 s42, s12, 2
	s_add_i32 s42, s42, s66
	s_mul_i32 s16, s42, 0x16000
	s_mul_hi_u32 s17, s42, 0x16000
	s_add_u32 s54, s50, s16
	s_addc_u32 s55, s51, s17
	s_mul_i32 s16, s5, 0x1600
	s_mul_hi_u32 s17, s5, 0x1600
	s_add_u32 s74, s90, s16
	s_addc_u32 s75, s91, s17
	s_lshl_b32 s16, s36, 8
	s_lshl_b32 s17, s70, 1
	s_add_i32 s16, s16, s17
	s_add_u32 s74, s74, s16
	s_addc_u32 s75, s75, 0
	s_add_u32 s12, s68, 0xb000
	s_addc_u32 s13, s69, 0
	global_load_dwordx4 v[98:101], v244, s[8:9]
	global_load_dwordx4 v[102:105], v244, s[68:69]
	global_load_dwordx4 v[106:109], v244, s[10:11]
	global_load_dwordx4 v[110:113], v244, s[12:13]
	global_load_dwordx4 v[114:117], v244, s[14:15]
	global_load_dwordx4 v[118:121], v244, s[8:9] offset:512
	global_load_dwordx4 v[122:125], v244, s[68:69] offset:512
	global_load_dwordx4 v[126:129], v244, s[10:11] offset:512
	global_load_dwordx4 v[138:141], v244, s[12:13] offset:512
	global_load_dwordx4 v[162:165], v244, s[14:15] offset:512
	v_cmp_eq_u32_e64 s[4:5], 0, v247
	v_cmp_eq_u32_e64 s[6:7], 15, v247
	v_mul_u32_u24_e32 v245, 0x5800, v247
	v_lshl_add_u32 v245, v248, 4, v245
	v_mov_b32_e32 v240, 0xbfb8aa3b
	v_mov_b32_e32 v241, 0xbfb8aa3b
	s_waitcnt vmcnt(0)
	v_cvt_f32_u32_e32 v242, v185
	v_cvt_f32_u32_e32 v243, v184
	v_fmamk_f32 v242, v242, 0x4f800000, v243
	v_fmamk_f32 v242, v242, 0x30800000, v251
	v_rsq_f32_e32 v224, v242
	v_cvt_f32_u32_e32 v242, v187
	v_cvt_f32_u32_e32 v243, v186
	v_fmamk_f32 v242, v242, 0x4f800000, v243
	v_fmamk_f32 v242, v242, 0x30800000, v251
	v_rsq_f32_e32 v225, v242
	v_cvt_f32_u32_e32 v242, v189
	v_cvt_f32_u32_e32 v243, v188
	v_fmamk_f32 v242, v242, 0x4f800000, v243
	v_fmamk_f32 v242, v242, 0x30800000, v251
	v_rsq_f32_e32 v226, v242
	v_cvt_f32_u32_e32 v242, v191
	v_cvt_f32_u32_e32 v243, v190
	v_fmamk_f32 v242, v242, 0x4f800000, v243
	v_fmamk_f32 v242, v242, 0x30800000, v251
	v_rsq_f32_e32 v227, v242
	v_cvt_f32_u32_e32 v242, v193
	v_cvt_f32_u32_e32 v243, v192
	v_fmamk_f32 v242, v242, 0x4f800000, v243
	v_fmamk_f32 v242, v242, 0x30800000, v251
	v_rsq_f32_e32 v228, v242
	v_cvt_f32_u32_e32 v242, v195
	v_cvt_f32_u32_e32 v243, v194
	v_fmamk_f32 v242, v242, 0x4f800000, v243
	v_fmamk_f32 v242, v242, 0x30800000, v251
	v_rsq_f32_e32 v229, v242
	v_cvt_f32_u32_e32 v242, v197
	v_cvt_f32_u32_e32 v243, v196
	v_fmamk_f32 v242, v242, 0x4f800000, v243
	v_fmamk_f32 v242, v242, 0x30800000, v251
	v_rsq_f32_e32 v230, v242
	v_cvt_f32_u32_e32 v242, v199
	v_cvt_f32_u32_e32 v243, v198
	v_fmamk_f32 v242, v242, 0x4f800000, v243
	v_fmamk_f32 v242, v242, 0x30800000, v251
	v_rsq_f32_e32 v231, v242
	global_load_dwordx4 v[184:187], v244, s[8:9] offset:16
	global_load_dwordx4 v[188:191], v244, s[68:69] offset:16
	global_load_dwordx4 v[192:195], v244, s[10:11] offset:16
	global_load_dwordx4 v[196:199], v244, s[12:13] offset:16
	global_load_dwordx4 v[200:203], v244, s[14:15] offset:16
	global_load_dwordx4 v[204:207], v244, s[8:9] offset:528
	global_load_dwordx4 v[208:211], v244, s[68:69] offset:528
	global_load_dwordx4 v[212:215], v244, s[10:11] offset:528
	global_load_dwordx4 v[216:219], v244, s[12:13] offset:528
	global_load_dwordx4 v[220:223], v244, s[14:15] offset:528
	v_pk_fma_f32 v[166:167], v[166:167], v[224:225], v[118:119] op_sel_hi:[1,0,1]
;     __device__ __forceinline__ void operator()(const f32x4 (&acc)[2][2][4][2], const Unit& u, int wr, int wc, int fr, int fq) const {
;     ...
;                 for (int bjr = 0; bjr < 2; ++bjr) { const int bj = 1 - bjr; const int co = bj * HALF + 4 * n;
;                     f32x4 U[4];
; #pragma unroll
;                     for (int m = 0; m < 4; ++m) U[m] = acc[ai][bj][m][n] * rs[ai][m] + prm[bj][0];
;                     if (fr < 2) *(f32x4*)(ep + (size_t)fr * NUP + co) = U[0];
;                     if (fr >= 14) *(f32x4*)(ep + (size_t)(fr - 12) * NUP + co) = U[3];
; #pragma unroll
;                     for (int m = 0; m < 4; ++m) { const f32x4 sp = (fr == 15 && m > 0) ? U[m > 0 ? m - 1 : 0] : U[m]; const f32x4 sn = (fr == 0 && m < 3) ? U[m < 3 ? m + 1 : 3] : U[m];
;                         f32x4 pv, nv;
; #pragma unroll
;                         for (int j = 0; j < 4; ++j) { pv[j] = __int_as_float(__builtin_amdgcn_update_dpp(0, __float_as_int(sp[j]), 0x121, 0xf, 0xf, false)); nv[j] = __int_as_float(__builtin_amdgcn_update_dpp(0, __float_as_int(sn[j]), 0x12F, 0xf, 0xf, false)); }
;                         const f32x4 R = prm[bj][1] * pv + prm[bj][2] * U[m] + prm[bj][3] * nv + prm[bj][4];
;                         if (bj == 1) {
; #pragma unroll
;                             for (int j = 0; j < 4; ++j) SG[m][j] = R[j] * __builtin_amdgcn_rcpf(1.0f + __expf(-R[j])); }
	v_pk_fma_f32 v[168:169], v[168:169], v[224:225], v[120:121] op_sel_hi:[1,0,1]
	v_pk_fma_f32 v[154:155], v[154:155], v[224:225], v[118:119] op_sel:[0,1,0] op_sel_hi:[1,1,1]
	v_pk_fma_f32 v[156:157], v[156:157], v[224:225], v[120:121] op_sel:[0,1,0] op_sel_hi:[1,1,1]
	v_pk_fma_f32 v[150:151], v[150:151], v[226:227], v[118:119] op_sel_hi:[1,0,1]
	v_pk_fma_f32 v[152:153], v[152:153], v[226:227], v[120:121] op_sel_hi:[1,0,1]
	v_pk_fma_f32 v[158:159], v[158:159], v[226:227], v[118:119] op_sel:[0,1,0] op_sel_hi:[1,1,1]
	v_pk_fma_f32 v[160:161], v[160:161], v[226:227], v[120:121] op_sel:[0,1,0] op_sel_hi:[1,1,1]
	s_mov_b64 exec, s[4:5]
	global_store_dwordx4 v244, v[166:169], s[54:55] offset:512
	s_add_u32 s16, s54, 0x5800
	s_addc_u32 s17, s55, 0
	global_store_dwordx4 v244, v[154:157], s[16:17] offset:512
	s_mov_b64 exec, s[6:7]
	s_add_u32 s56, s54, 0xb000
	s_addc_u32 s57, s55, 0
	global_store_dwordx4 v244, v[150:153], s[56:57] offset:512
	s_add_u32 s16, s54, 0x10800
	s_addc_u32 s17, s55, 0
	global_store_dwordx4 v244, v[158:161], s[16:17] offset:512
	s_mov_b64 exec, -1
	v_pk_fma_f32 v[232:233], v[126:127], v[166:167], v[162:163]
	v_pk_fma_f32 v[234:235], v[126:127], v[154:155], v[162:163]
	v_pk_fma_f32 v[236:237], v[126:127], v[150:151], v[162:163]
	v_pk_fma_f32 v[238:239], v[126:127], v[158:159], v[162:163]
	v_pk_fma_f32 v[234:235], v[122:123], v[166:167], v[234:235]
	v_pk_fma_f32 v[236:237], v[122:123], v[154:155], v[236:237]
	v_pk_fma_f32 v[238:239], v[122:123], v[150:151], v[238:239]
	v_pk_fma_f32 v[232:233], v[138:139], v[154:155], v[232:233]
	v_pk_fma_f32 v[234:235], v[138:139], v[150:151], v[234:235]
	v_pk_fma_f32 v[236:237], v[138:139], v[158:159], v[236:237]
	v_fmac_f32_dpp v232, v158, v122 row_ror:1 row_mask:0xf bank_mask:0xf
	v_fmac_f32_dpp v233, v159, v123 row_ror:1 row_mask:0xf bank_mask:0xf
	v_fmac_f32_dpp v238, v166, v138 row_ror:15 row_mask:0xf bank_mask:0xf
	v_fmac_f32_dpp v239, v167, v139 row_ror:15 row_mask:0xf bank_mask:0xf
	v_pk_mul_f32 v[166:167], v[232:233], v[240:241]
	v_pk_mul_f32 v[154:155], v[234:235], v[240:241]
	v_pk_mul_f32 v[150:151], v[236:237], v[240:241]
	v_pk_mul_f32 v[158:159], v[238:239], v[240:241]
	v_exp_f32_e32 v166, v166
	v_exp_f32_e32 v167, v167
	v_exp_f32_e32 v154, v154
	v_exp_f32_e32 v155, v155
	v_exp_f32_e32 v150, v150
	v_exp_f32_e32 v151, v151
	v_exp_f32_e32 v158, v158
	v_exp_f32_e32 v159, v159
	v_add_f32_e32 v166, 1.0, v166
	v_add_f32_e32 v167, 1.0, v167
	v_add_f32_e32 v154, 1.0, v154
	v_add_f32_e32 v155, 1.0, v155
	v_add_f32_e32 v150, 1.0, v150
	v_add_f32_e32 v151, 1.0, v151
	v_add_f32_e32 v158, 1.0, v158
	v_add_f32_e32 v159, 1.0, v159
	v_rcp_f32_e32 v166, v166
	v_rcp_f32_e32 v167, v167
	v_rcp_f32_e32 v154, v154
	v_rcp_f32_e32 v155, v155
	v_rcp_f32_e32 v150, v150
	v_rcp_f32_e32 v151, v151
	v_rcp_f32_e32 v158, v158
	v_rcp_f32_e32 v159, v159
	v_pk_mul_f32 v[166:167], v[232:233], v[166:167]
	v_pk_mul_f32 v[154:155], v[234:235], v[154:155]
	v_pk_mul_f32 v[150:151], v[236:237], v[150:151]
	v_pk_mul_f32 v[158:159], v[238:239], v[158:159]
	v_pk_fma_f32 v[232:233], v[128:129], v[168:169], v[164:165]
	v_pk_fma_f32 v[234:235], v[128:129], v[156:157], v[164:165]
	v_pk_fma_f32 v[236:237], v[128:129], v[152:153], v[164:165]
	v_pk_fma_f32 v[238:239], v[128:129], v[160:161], v[164:165]
	v_pk_fma_f32 v[234:235], v[124:125], v[168:169], v[234:235]
	v_pk_fma_f32 v[236:237], v[124:125], v[156:157], v[236:237]
	v_pk_fma_f32 v[238:239], v[124:125], v[152:153], v[238:239]
	v_pk_fma_f32 v[232:233], v[140:141], v[156:157], v[232:233]
	v_pk_fma_f32 v[234:235], v[140:141], v[152:153], v[234:235]
	v_pk_fma_f32 v[236:237], v[140:141], v[160:161], v[236:237]
	v_fmac_f32_dpp v232, v160, v124 row_ror:1 row_mask:0xf bank_mask:0xf
	v_fmac_f32_dpp v233, v161, v125 row_ror:1 row_mask:0xf bank_mask:0xf
	v_fmac_f32_dpp v238, v168, v140 row_ror:15 row_mask:0xf bank_mask:0xf
	v_fmac_f32_dpp v239, v169, v141 row_ror:15 row_mask:0xf bank_mask:0xf
	v_pk_mul_f32 v[168:169], v[232:233], v[240:241]
	v_pk_mul_f32 v[156:157], v[234:235], v[240:241]
	v_pk_mul_f32 v[152:153], v[236:237], v[240:241]
	v_pk_mul_f32 v[160:161], v[238:239], v[240:241]
	v_exp_f32_e32 v168, v168
	v_exp_f32_e32 v169, v169
	v_exp_f32_e32 v156, v156
	v_exp_f32_e32 v157, v157
	v_exp_f32_e32 v152, v152
	v_exp_f32_e32 v153, v153
	v_exp_f32_e32 v160, v160
	v_exp_f32_e32 v161, v161
	v_add_f32_e32 v168, 1.0, v168
	v_add_f32_e32 v169, 1.0, v169
	v_add_f32_e32 v156, 1.0, v156
	v_add_f32_e32 v157, 1.0, v157
	v_add_f32_e32 v152, 1.0, v152
	v_add_f32_e32 v153, 1.0, v153
	v_add_f32_e32 v160, 1.0, v160
	v_add_f32_e32 v161, 1.0, v161
	v_rcp_f32_e32 v168, v168
	v_rcp_f32_e32 v169, v169
	v_rcp_f32_e32 v156, v156
	v_rcp_f32_e32 v157, v157
	v_rcp_f32_e32 v152, v152
	v_rcp_f32_e32 v153, v153
	v_rcp_f32_e32 v160, v160
	v_rcp_f32_e32 v161, v161
	v_pk_mul_f32 v[168:169], v[232:233], v[168:169]
	v_pk_mul_f32 v[156:157], v[234:235], v[156:157]
	v_pk_mul_f32 v[152:153], v[236:237], v[152:153]
	v_pk_mul_f32 v[160:161], v[238:239], v[160:161]
	v_pk_fma_f32 v[146:147], v[146:147], v[224:225], v[98:99] op_sel_hi:[1,0,1]
	v_pk_fma_f32 v[148:149], v[148:149], v[224:225], v[100:101] op_sel_hi:[1,0,1]
	v_pk_fma_f32 v[134:135], v[134:135], v[224:225], v[98:99] op_sel:[0,1,0] op_sel_hi:[1,1,1]
	v_pk_fma_f32 v[136:137], v[136:137], v[224:225], v[100:101] op_sel:[0,1,0] op_sel_hi:[1,1,1]
	v_pk_fma_f32 v[130:131], v[130:131], v[226:227], v[98:99] op_sel_hi:[1,0,1]
	v_pk_fma_f32 v[132:133], v[132:133], v[226:227], v[100:101] op_sel_hi:[1,0,1]
	v_pk_fma_f32 v[142:143], v[142:143], v[226:227], v[98:99] op_sel:[0,1,0] op_sel_hi:[1,1,1]
	v_pk_fma_f32 v[144:145], v[144:145], v[226:227], v[100:101] op_sel:[0,1,0] op_sel_hi:[1,1,1]
; __device__ __forceinline__ unsigned cvt_pk_bf16_asm(float lo, float hi) { unsigned r; asm volatile("v_cvt_pk_bf16_f32 %0, %1, %2" : "=v"(r) : "v"(lo), "v"(hi)); return r; }
;     __device__ __forceinline__ void operator()(const f32x4 (&acc)[2][2][4][2], const Unit& u, int wr, int wc, int fr, int fq) const {
;     ...
;                     for (int m = 0; m < 4; ++m) U[m] = acc[ai][bj][m][n] * rs[ai][m] + prm[bj][0];
;                     if (fr < 2) *(f32x4*)(ep + (size_t)fr * NUP + co) = U[0];
;                     if (fr >= 14) *(f32x4*)(ep + (size_t)(fr - 12) * NUP + co) = U[3];
; #pragma unroll
;                     for (int m = 0; m < 4; ++m) { const f32x4 sp = (fr == 15 && m > 0) ? U[m > 0 ? m - 1 : 0] : U[m]; const f32x4 sn = (fr == 0 && m < 3) ? U[m < 3 ? m + 1 : 3] : U[m];
;                         f32x4 pv, nv;
; #pragma unroll
;                         for (int j = 0; j < 4; ++j) { pv[j] = __int_as_float(__builtin_amdgcn_update_dpp(0, __float_as_int(sp[j]), 0x121, 0xf, 0xf, false)); nv[j] = __int_as_float(__builtin_amdgcn_update_dpp(0, __float_as_int(sn[j]), 0x12F, 0xf, 0xf, false)); }
;                         const f32x4 R = prm[bj][1] * pv + prm[bj][2] * U[m] + prm[bj][3] * nv + prm[bj][4];
;                         if (bj == 1) {
; #pragma unroll
;                             for (int j = 0; j < 4; ++j) SG[m][j] = R[j] * __builtin_amdgcn_rcpf(1.0f + __expf(-R[j])); }
;                         else { const int r = row0 + ai * HALF + m * 16; const bool skip = (m == 0 && fr == 0) || (m == 3 && fr == 15);
;                             const f32x4 o = R * SG[m]; u32x2 w; w.x = cvt_pk_bf16_asm(o[0], o[1]); w.y = cvt_pk_bf16_asm(o[2], o[3]);
;                             if (!skip) *(u32x2*)(act + (size_t)r * FFD + u.pn * 128 + wc * 32 + 8 * fq + 4 * n) = w; } } } }
	s_mov_b64 exec, s[4:5]
	global_store_dwordx4 v244, v[146:149], s[54:55]
	s_add_u32 s16, s54, 0x5800
	s_addc_u32 s17, s55, 0
	global_store_dwordx4 v244, v[134:137], s[16:17]
	s_mov_b64 exec, s[6:7]
	s_add_u32 s56, s54, 0xb000
	s_addc_u32 s57, s55, 0
	global_store_dwordx4 v244, v[130:133], s[56:57]
	s_add_u32 s16, s54, 0x10800
	s_addc_u32 s17, s55, 0
	global_store_dwordx4 v244, v[142:145], s[16:17]
	s_mov_b64 exec, -1
	v_pk_fma_f32 v[232:233], v[106:107], v[146:147], v[114:115]
	v_pk_fma_f32 v[234:235], v[106:107], v[134:135], v[114:115]
	v_pk_fma_f32 v[236:237], v[106:107], v[130:131], v[114:115]
	v_pk_fma_f32 v[238:239], v[106:107], v[142:143], v[114:115]
	v_pk_fma_f32 v[234:235], v[102:103], v[146:147], v[234:235]
	v_pk_fma_f32 v[236:237], v[102:103], v[134:135], v[236:237]
	v_pk_fma_f32 v[238:239], v[102:103], v[130:131], v[238:239]
	v_pk_fma_f32 v[232:233], v[110:111], v[134:135], v[232:233]
	v_pk_fma_f32 v[234:235], v[110:111], v[130:131], v[234:235]
	v_pk_fma_f32 v[236:237], v[110:111], v[142:143], v[236:237]
	v_fmac_f32_dpp v232, v142, v102 row_ror:1 row_mask:0xf bank_mask:0xf
	v_fmac_f32_dpp v233, v143, v103 row_ror:1 row_mask:0xf bank_mask:0xf
	v_fmac_f32_dpp v238, v146, v110 row_ror:15 row_mask:0xf bank_mask:0xf
	v_fmac_f32_dpp v239, v147, v111 row_ror:15 row_mask:0xf bank_mask:0xf
	v_pk_mul_f32 v[232:233], v[232:233], v[166:167]
	v_pk_mul_f32 v[234:235], v[234:235], v[154:155]
	v_pk_mul_f32 v[236:237], v[236:237], v[150:151]
	v_pk_mul_f32 v[238:239], v[238:239], v[158:159]
	v_cvt_pk_bf16_f32 v146, v232, v233
	v_cvt_pk_bf16_f32 v134, v234, v235
	v_cvt_pk_bf16_f32 v130, v236, v237
	v_cvt_pk_bf16_f32 v142, v238, v239
	v_pk_fma_f32 v[232:233], v[108:109], v[148:149], v[116:117]
	v_pk_fma_f32 v[234:235], v[108:109], v[136:137], v[116:117]
	v_pk_fma_f32 v[236:237], v[108:109], v[132:133], v[116:117]
	v_pk_fma_f32 v[238:239], v[108:109], v[144:145], v[116:117]
	v_pk_fma_f32 v[234:235], v[104:105], v[148:149], v[234:235]
	v_pk_fma_f32 v[236:237], v[104:105], v[136:137], v[236:237]
	v_pk_fma_f32 v[238:239], v[104:105], v[132:133], v[238:239]
	v_pk_fma_f32 v[232:233], v[112:113], v[136:137], v[232:233]
	v_pk_fma_f32 v[234:235], v[112:113], v[132:133], v[234:235]
	v_pk_fma_f32 v[236:237], v[112:113], v[144:145], v[236:237]
	v_fmac_f32_dpp v232, v144, v104 row_ror:1 row_mask:0xf bank_mask:0xf
	v_fmac_f32_dpp v233, v145, v105 row_ror:1 row_mask:0xf bank_mask:0xf
	v_fmac_f32_dpp v238, v148, v112 row_ror:15 row_mask:0xf bank_mask:0xf
	v_fmac_f32_dpp v239, v149, v113 row_ror:15 row_mask:0xf bank_mask:0xf
	v_pk_mul_f32 v[232:233], v[232:233], v[168:169]
	v_pk_mul_f32 v[234:235], v[234:235], v[156:157]
	v_pk_mul_f32 v[236:237], v[236:237], v[152:153]
	v_pk_mul_f32 v[238:239], v[238:239], v[160:161]
	v_cvt_pk_bf16_f32 v147, v232, v233
	v_cvt_pk_bf16_f32 v135, v234, v235
	v_cvt_pk_bf16_f32 v131, v236, v237
	v_cvt_pk_bf16_f32 v143, v238, v239
	s_add_u32 s54, s54, 0x2c000
	s_addc_u32 s55, s55, 0
	v_pk_fma_f32 v[94:95], v[94:95], v[228:229], v[118:119] op_sel_hi:[1,0,1]
	v_pk_fma_f32 v[96:97], v[96:97], v[228:229], v[120:121] op_sel_hi:[1,0,1]
	v_pk_fma_f32 v[86:87], v[86:87], v[228:229], v[118:119] op_sel:[0,1,0] op_sel_hi:[1,1,1]
	v_pk_fma_f32 v[88:89], v[88:89], v[228:229], v[120:121] op_sel:[0,1,0] op_sel_hi:[1,1,1]
	v_pk_fma_f32 v[82:83], v[82:83], v[230:231], v[118:119] op_sel_hi:[1,0,1]
	v_pk_fma_f32 v[84:85], v[84:85], v[230:231], v[120:121] op_sel_hi:[1,0,1]
	v_pk_fma_f32 v[90:91], v[90:91], v[230:231], v[118:119] op_sel:[0,1,0] op_sel_hi:[1,1,1]
	v_pk_fma_f32 v[92:93], v[92:93], v[230:231], v[120:121] op_sel:[0,1,0] op_sel_hi:[1,1,1]
	s_mov_b64 exec, s[4:5]
	global_store_dwordx4 v244, v[94:97], s[54:55] offset:512
	s_add_u32 s16, s54, 0x5800
	s_addc_u32 s17, s55, 0
	global_store_dwordx4 v244, v[86:89], s[16:17] offset:512
	s_mov_b64 exec, s[6:7]
	s_add_u32 s56, s54, 0xb000
	s_addc_u32 s57, s55, 0
	global_store_dwordx4 v244, v[82:85], s[56:57] offset:512
	s_add_u32 s16, s54, 0x10800
	s_addc_u32 s17, s55, 0
	global_store_dwordx4 v244, v[90:93], s[16:17] offset:512
	s_mov_b64 exec, -1
	v_pk_fma_f32 v[232:233], v[126:127], v[94:95], v[162:163]
	v_pk_fma_f32 v[234:235], v[126:127], v[86:87], v[162:163]
	v_pk_fma_f32 v[236:237], v[126:127], v[82:83], v[162:163]
	v_pk_fma_f32 v[238:239], v[126:127], v[90:91], v[162:163]
	v_pk_fma_f32 v[234:235], v[122:123], v[94:95], v[234:235]
	v_pk_fma_f32 v[236:237], v[122:123], v[86:87], v[236:237]
	v_pk_fma_f32 v[238:239], v[122:123], v[82:83], v[238:239]
	v_pk_fma_f32 v[232:233], v[138:139], v[86:87], v[232:233]
	v_pk_fma_f32 v[234:235], v[138:139], v[82:83], v[234:235]
	v_pk_fma_f32 v[236:237], v[138:139], v[90:91], v[236:237]
	v_fmac_f32_dpp v232, v90, v122 row_ror:1 row_mask:0xf bank_mask:0xf
	v_fmac_f32_dpp v233, v91, v123 row_ror:1 row_mask:0xf bank_mask:0xf
	v_fmac_f32_dpp v238, v94, v138 row_ror:15 row_mask:0xf bank_mask:0xf
	v_fmac_f32_dpp v239, v95, v139 row_ror:15 row_mask:0xf bank_mask:0xf
	v_pk_mul_f32 v[94:95], v[232:233], v[240:241]
	v_pk_mul_f32 v[86:87], v[234:235], v[240:241]
	v_pk_mul_f32 v[82:83], v[236:237], v[240:241]
	v_pk_mul_f32 v[90:91], v[238:239], v[240:241]
	v_exp_f32_e32 v94, v94
	v_exp_f32_e32 v95, v95
	v_exp_f32_e32 v86, v86
	v_exp_f32_e32 v87, v87
	v_exp_f32_e32 v82, v82
	v_exp_f32_e32 v83, v83
	v_exp_f32_e32 v90, v90
	v_exp_f32_e32 v91, v91
	v_add_f32_e32 v94, 1.0, v94
	v_add_f32_e32 v95, 1.0, v95
	v_add_f32_e32 v86, 1.0, v86
	v_add_f32_e32 v87, 1.0, v87
	v_add_f32_e32 v82, 1.0, v82
	v_add_f32_e32 v83, 1.0, v83
	v_add_f32_e32 v90, 1.0, v90
	v_add_f32_e32 v91, 1.0, v91
	v_rcp_f32_e32 v94, v94
	v_rcp_f32_e32 v95, v95
	v_rcp_f32_e32 v86, v86
	v_rcp_f32_e32 v87, v87
; __device__ __forceinline__ unsigned cvt_pk_bf16_asm(float lo, float hi) { unsigned r; asm volatile("v_cvt_pk_bf16_f32 %0, %1, %2" : "=v"(r) : "v"(lo), "v"(hi)); return r; }
;     __device__ __forceinline__ void operator()(const f32x4 (&acc)[2][2][4][2], const Unit& u, int wr, int wc, int fr, int fq) const {
;     ...
;                     for (int m = 0; m < 4; ++m) U[m] = acc[ai][bj][m][n] * rs[ai][m] + prm[bj][0];
;                     if (fr < 2) *(f32x4*)(ep + (size_t)fr * NUP + co) = U[0];
;                     if (fr >= 14) *(f32x4*)(ep + (size_t)(fr - 12) * NUP + co) = U[3];
; #pragma unroll
;                     for (int m = 0; m < 4; ++m) { const f32x4 sp = (fr == 15 && m > 0) ? U[m > 0 ? m - 1 : 0] : U[m]; const f32x4 sn = (fr == 0 && m < 3) ? U[m < 3 ? m + 1 : 3] : U[m];
;                         f32x4 pv, nv;
; #pragma unroll
;                         for (int j = 0; j < 4; ++j) { pv[j] = __int_as_float(__builtin_amdgcn_update_dpp(0, __float_as_int(sp[j]), 0x121, 0xf, 0xf, false)); nv[j] = __int_as_float(__builtin_amdgcn_update_dpp(0, __float_as_int(sn[j]), 0x12F, 0xf, 0xf, false)); }
;                         const f32x4 R = prm[bj][1] * pv + prm[bj][2] * U[m] + prm[bj][3] * nv + prm[bj][4];
;                         if (bj == 1) {
; #pragma unroll
;                             for (int j = 0; j < 4; ++j) SG[m][j] = R[j] * __builtin_amdgcn_rcpf(1.0f + __expf(-R[j])); }
;                         else { const int r = row0 + ai * HALF + m * 16; const bool skip = (m == 0 && fr == 0) || (m == 3 && fr == 15);
;                             const f32x4 o = R * SG[m]; u32x2 w; w.x = cvt_pk_bf16_asm(o[0], o[1]); w.y = cvt_pk_bf16_asm(o[2], o[3]);
;                             if (!skip) *(u32x2*)(act + (size_t)r * FFD + u.pn * 128 + wc * 32 + 8 * fq + 4 * n) = w; } } } }
	v_rcp_f32_e32 v82, v82
	v_rcp_f32_e32 v83, v83
	v_rcp_f32_e32 v90, v90
	v_rcp_f32_e32 v91, v91
	v_pk_mul_f32 v[94:95], v[232:233], v[94:95]
	v_pk_mul_f32 v[86:87], v[234:235], v[86:87]
	v_pk_mul_f32 v[82:83], v[236:237], v[82:83]
	v_pk_mul_f32 v[90:91], v[238:239], v[90:91]
	v_pk_fma_f32 v[232:233], v[128:129], v[96:97], v[164:165]
	v_pk_fma_f32 v[234:235], v[128:129], v[88:89], v[164:165]
	v_pk_fma_f32 v[236:237], v[128:129], v[84:85], v[164:165]
	v_pk_fma_f32 v[238:239], v[128:129], v[92:93], v[164:165]
	v_pk_fma_f32 v[234:235], v[124:125], v[96:97], v[234:235]
	v_pk_fma_f32 v[236:237], v[124:125], v[88:89], v[236:237]
	v_pk_fma_f32 v[238:239], v[124:125], v[84:85], v[238:239]
	v_pk_fma_f32 v[232:233], v[140:141], v[88:89], v[232:233]
	v_pk_fma_f32 v[234:235], v[140:141], v[84:85], v[234:235]
	v_pk_fma_f32 v[236:237], v[140:141], v[92:93], v[236:237]
	v_fmac_f32_dpp v232, v92, v124 row_ror:1 row_mask:0xf bank_mask:0xf
	v_fmac_f32_dpp v233, v93, v125 row_ror:1 row_mask:0xf bank_mask:0xf
	v_fmac_f32_dpp v238, v96, v140 row_ror:15 row_mask:0xf bank_mask:0xf
	v_fmac_f32_dpp v239, v97, v141 row_ror:15 row_mask:0xf bank_mask:0xf
	v_pk_mul_f32 v[96:97], v[232:233], v[240:241]
	v_pk_mul_f32 v[88:89], v[234:235], v[240:241]
	v_pk_mul_f32 v[84:85], v[236:237], v[240:241]
	v_pk_mul_f32 v[92:93], v[238:239], v[240:241]
	v_exp_f32_e32 v96, v96
	v_exp_f32_e32 v97, v97
	v_exp_f32_e32 v88, v88
	v_exp_f32_e32 v89, v89
	v_exp_f32_e32 v84, v84
	v_exp_f32_e32 v85, v85
	v_exp_f32_e32 v92, v92
	v_exp_f32_e32 v93, v93
	v_add_f32_e32 v96, 1.0, v96
	v_add_f32_e32 v97, 1.0, v97
	v_add_f32_e32 v88, 1.0, v88
	v_add_f32_e32 v89, 1.0, v89
	v_add_f32_e32 v84, 1.0, v84
	v_add_f32_e32 v85, 1.0, v85
	v_add_f32_e32 v92, 1.0, v92
	v_add_f32_e32 v93, 1.0, v93
	v_rcp_f32_e32 v96, v96
	v_rcp_f32_e32 v97, v97
	v_rcp_f32_e32 v88, v88
	v_rcp_f32_e32 v89, v89
	v_rcp_f32_e32 v84, v84
	v_rcp_f32_e32 v85, v85
	v_rcp_f32_e32 v92, v92
	v_rcp_f32_e32 v93, v93
	v_pk_mul_f32 v[96:97], v[232:233], v[96:97]
	v_pk_mul_f32 v[88:89], v[234:235], v[88:89]
	v_pk_mul_f32 v[84:85], v[236:237], v[84:85]
	v_pk_mul_f32 v[92:93], v[238:239], v[92:93]
	v_pk_fma_f32 v[78:79], v[78:79], v[228:229], v[98:99] op_sel_hi:[1,0,1]
	v_pk_fma_f32 v[80:81], v[80:81], v[228:229], v[100:101] op_sel_hi:[1,0,1]
	v_pk_fma_f32 v[70:71], v[70:71], v[228:229], v[98:99] op_sel:[0,1,0] op_sel_hi:[1,1,1]
	v_pk_fma_f32 v[72:73], v[72:73], v[228:229], v[100:101] op_sel:[0,1,0] op_sel_hi:[1,1,1]
	v_pk_fma_f32 v[66:67], v[66:67], v[230:231], v[98:99] op_sel_hi:[1,0,1]
	v_pk_fma_f32 v[68:69], v[68:69], v[230:231], v[100:101] op_sel_hi:[1,0,1]
	v_pk_fma_f32 v[74:75], v[74:75], v[230:231], v[98:99] op_sel:[0,1,0] op_sel_hi:[1,1,1]
	v_pk_fma_f32 v[76:77], v[76:77], v[230:231], v[100:101] op_sel:[0,1,0] op_sel_hi:[1,1,1]
	s_mov_b64 exec, s[4:5]
	global_store_dwordx4 v244, v[78:81], s[54:55]
	s_add_u32 s16, s54, 0x5800
	s_addc_u32 s17, s55, 0
	global_store_dwordx4 v244, v[70:73], s[16:17]
	s_mov_b64 exec, s[6:7]
	s_add_u32 s56, s54, 0xb000
	s_addc_u32 s57, s55, 0
	global_store_dwordx4 v244, v[66:69], s[56:57]
	s_add_u32 s16, s54, 0x10800
	s_addc_u32 s17, s55, 0
	global_store_dwordx4 v244, v[74:77], s[16:17]
	s_mov_b64 exec, -1
	v_pk_fma_f32 v[232:233], v[106:107], v[78:79], v[114:115]
	v_pk_fma_f32 v[234:235], v[106:107], v[70:71], v[114:115]
	v_pk_fma_f32 v[236:237], v[106:107], v[66:67], v[114:115]
	v_pk_fma_f32 v[238:239], v[106:107], v[74:75], v[114:115]
	v_pk_fma_f32 v[234:235], v[102:103], v[78:79], v[234:235]
	v_pk_fma_f32 v[236:237], v[102:103], v[70:71], v[236:237]
	v_pk_fma_f32 v[238:239], v[102:103], v[66:67], v[238:239]
	v_pk_fma_f32 v[232:233], v[110:111], v[70:71], v[232:233]
	v_pk_fma_f32 v[234:235], v[110:111], v[66:67], v[234:235]
	v_pk_fma_f32 v[236:237], v[110:111], v[74:75], v[236:237]
	v_fmac_f32_dpp v232, v74, v102 row_ror:1 row_mask:0xf bank_mask:0xf
	v_fmac_f32_dpp v233, v75, v103 row_ror:1 row_mask:0xf bank_mask:0xf
	v_fmac_f32_dpp v238, v78, v110 row_ror:15 row_mask:0xf bank_mask:0xf
	v_fmac_f32_dpp v239, v79, v111 row_ror:15 row_mask:0xf bank_mask:0xf
	v_pk_mul_f32 v[232:233], v[232:233], v[94:95]
	v_pk_mul_f32 v[234:235], v[234:235], v[86:87]
	v_pk_mul_f32 v[236:237], v[236:237], v[82:83]
	v_pk_mul_f32 v[238:239], v[238:239], v[90:91]
	v_cvt_pk_bf16_f32 v78, v232, v233
	v_cvt_pk_bf16_f32 v70, v234, v235
	v_cvt_pk_bf16_f32 v66, v236, v237
	v_cvt_pk_bf16_f32 v74, v238, v239
	v_pk_fma_f32 v[232:233], v[108:109], v[80:81], v[116:117]
	v_pk_fma_f32 v[234:235], v[108:109], v[72:73], v[116:117]
	v_pk_fma_f32 v[236:237], v[108:109], v[68:69], v[116:117]
	v_pk_fma_f32 v[238:239], v[108:109], v[76:77], v[116:117]
	v_pk_fma_f32 v[234:235], v[104:105], v[80:81], v[234:235]
	v_pk_fma_f32 v[236:237], v[104:105], v[72:73], v[236:237]
	v_pk_fma_f32 v[238:239], v[104:105], v[68:69], v[238:239]
	v_pk_fma_f32 v[232:233], v[112:113], v[72:73], v[232:233]
	v_pk_fma_f32 v[234:235], v[112:113], v[68:69], v[234:235]
	v_pk_fma_f32 v[236:237], v[112:113], v[76:77], v[236:237]
	v_fmac_f32_dpp v232, v76, v104 row_ror:1 row_mask:0xf bank_mask:0xf
	v_fmac_f32_dpp v233, v77, v105 row_ror:1 row_mask:0xf bank_mask:0xf
	v_fmac_f32_dpp v238, v80, v112 row_ror:15 row_mask:0xf bank_mask:0xf
	v_fmac_f32_dpp v239, v81, v113 row_ror:15 row_mask:0xf bank_mask:0xf
	v_pk_mul_f32 v[232:233], v[232:233], v[96:97]
	v_pk_mul_f32 v[234:235], v[234:235], v[88:89]
	v_pk_mul_f32 v[236:237], v[236:237], v[84:85]
	v_pk_mul_f32 v[238:239], v[238:239], v[92:93]
	v_cvt_pk_bf16_f32 v79, v232, v233
	v_cvt_pk_bf16_f32 v71, v234, v235
	v_cvt_pk_bf16_f32 v67, v236, v237
	v_cvt_pk_bf16_f32 v75, v238, v239
	s_waitcnt vmcnt(16)
;     __device__ __forceinline__ void operator()(const f32x4 (&acc)[2][2][4][2], const Unit& u, int wr, int wc, int fr, int fq) const {
;     ...
;                 for (int bjr = 0; bjr < 2; ++bjr) { const int bj = 1 - bjr; const int co = bj * HALF + 4 * n;
;                     f32x4 U[4];
; #pragma unroll
;                     for (int m = 0; m < 4; ++m) U[m] = acc[ai][bj][m][n] * rs[ai][m] + prm[bj][0];
;                     if (fr < 2) *(f32x4*)(ep + (size_t)fr * NUP + co) = U[0];
;                     if (fr >= 14) *(f32x4*)(ep + (size_t)(fr - 12) * NUP + co) = U[3];
; #pragma unroll
;                     for (int m = 0; m < 4; ++m) { const f32x4 sp = (fr == 15 && m > 0) ? U[m > 0 ? m - 1 : 0] : U[m]; const f32x4 sn = (fr == 0 && m < 3) ? U[m < 3 ? m + 1 : 3] : U[m];
;                         f32x4 pv, nv;
; #pragma unroll
;                         for (int j = 0; j < 4; ++j) { pv[j] = __int_as_float(__builtin_amdgcn_update_dpp(0, __float_as_int(sp[j]), 0x121, 0xf, 0xf, false)); nv[j] = __int_as_float(__builtin_amdgcn_update_dpp(0, __float_as_int(sn[j]), 0x12F, 0xf, 0xf, false)); }
;                         const f32x4 R = prm[bj][1] * pv + prm[bj][2] * U[m] + prm[bj][3] * nv + prm[bj][4];
;                         if (bj == 1) {
; #pragma unroll
;                             for (int j = 0; j < 4; ++j) SG[m][j] = R[j] * __builtin_amdgcn_rcpf(1.0f + __expf(-R[j])); }
	s_sub_u32 s54, s54, 0x2c000
	s_subb_u32 s55, s55, 0
	v_pk_fma_f32 v[62:63], v[62:63], v[224:225], v[204:205] op_sel_hi:[1,0,1]
	v_pk_fma_f32 v[64:65], v[64:65], v[224:225], v[206:207] op_sel_hi:[1,0,1]
	v_pk_fma_f32 v[54:55], v[54:55], v[224:225], v[204:205] op_sel:[0,1,0] op_sel_hi:[1,1,1]
	v_pk_fma_f32 v[56:57], v[56:57], v[224:225], v[206:207] op_sel:[0,1,0] op_sel_hi:[1,1,1]
	v_pk_fma_f32 v[50:51], v[50:51], v[226:227], v[204:205] op_sel_hi:[1,0,1]
	v_pk_fma_f32 v[52:53], v[52:53], v[226:227], v[206:207] op_sel_hi:[1,0,1]
	v_pk_fma_f32 v[58:59], v[58:59], v[226:227], v[204:205] op_sel:[0,1,0] op_sel_hi:[1,1,1]
	v_pk_fma_f32 v[60:61], v[60:61], v[226:227], v[206:207] op_sel:[0,1,0] op_sel_hi:[1,1,1]
	s_mov_b64 exec, s[4:5]
	global_store_dwordx4 v244, v[62:65], s[54:55] offset:528
	s_add_u32 s16, s54, 0x5800
	s_addc_u32 s17, s55, 0
	global_store_dwordx4 v244, v[54:57], s[16:17] offset:528
	s_mov_b64 exec, s[6:7]
	s_add_u32 s56, s54, 0xb000
	s_addc_u32 s57, s55, 0
	global_store_dwordx4 v244, v[50:53], s[56:57] offset:528
	s_add_u32 s16, s54, 0x10800
	s_addc_u32 s17, s55, 0
	global_store_dwordx4 v244, v[58:61], s[16:17] offset:528
	s_mov_b64 exec, -1
	v_pk_fma_f32 v[232:233], v[212:213], v[62:63], v[220:221]
	v_pk_fma_f32 v[234:235], v[212:213], v[54:55], v[220:221]
	v_pk_fma_f32 v[236:237], v[212:213], v[50:51], v[220:221]
	v_pk_fma_f32 v[238:239], v[212:213], v[58:59], v[220:221]
	v_pk_fma_f32 v[234:235], v[208:209], v[62:63], v[234:235]
	v_pk_fma_f32 v[236:237], v[208:209], v[54:55], v[236:237]
	v_pk_fma_f32 v[238:239], v[208:209], v[50:51], v[238:239]
	v_pk_fma_f32 v[232:233], v[216:217], v[54:55], v[232:233]
	v_pk_fma_f32 v[234:235], v[216:217], v[50:51], v[234:235]
	v_pk_fma_f32 v[236:237], v[216:217], v[58:59], v[236:237]
	v_fmac_f32_dpp v232, v58, v208 row_ror:1 row_mask:0xf bank_mask:0xf
	v_fmac_f32_dpp v233, v59, v209 row_ror:1 row_mask:0xf bank_mask:0xf
	v_fmac_f32_dpp v238, v62, v216 row_ror:15 row_mask:0xf bank_mask:0xf
	v_fmac_f32_dpp v239, v63, v217 row_ror:15 row_mask:0xf bank_mask:0xf
	v_pk_mul_f32 v[62:63], v[232:233], v[240:241]
	v_pk_mul_f32 v[54:55], v[234:235], v[240:241]
	v_pk_mul_f32 v[50:51], v[236:237], v[240:241]
	v_pk_mul_f32 v[58:59], v[238:239], v[240:241]
	v_exp_f32_e32 v62, v62
	v_exp_f32_e32 v63, v63
	v_exp_f32_e32 v54, v54
	v_exp_f32_e32 v55, v55
	v_exp_f32_e32 v50, v50
	v_exp_f32_e32 v51, v51
	v_exp_f32_e32 v58, v58
	v_exp_f32_e32 v59, v59
	v_add_f32_e32 v62, 1.0, v62
	v_add_f32_e32 v63, 1.0, v63
	v_add_f32_e32 v54, 1.0, v54
	v_add_f32_e32 v55, 1.0, v55
	v_add_f32_e32 v50, 1.0, v50
	v_add_f32_e32 v51, 1.0, v51
	v_add_f32_e32 v58, 1.0, v58
	v_add_f32_e32 v59, 1.0, v59
	v_rcp_f32_e32 v62, v62
	v_rcp_f32_e32 v63, v63
	v_rcp_f32_e32 v54, v54
	v_rcp_f32_e32 v55, v55
	v_rcp_f32_e32 v50, v50
	v_rcp_f32_e32 v51, v51
	v_rcp_f32_e32 v58, v58
	v_rcp_f32_e32 v59, v59
	v_pk_mul_f32 v[62:63], v[232:233], v[62:63]
	v_pk_mul_f32 v[54:55], v[234:235], v[54:55]
	v_pk_mul_f32 v[50:51], v[236:237], v[50:51]
	v_pk_mul_f32 v[58:59], v[238:239], v[58:59]
	v_pk_fma_f32 v[232:233], v[214:215], v[64:65], v[222:223]
	v_pk_fma_f32 v[234:235], v[214:215], v[56:57], v[222:223]
	v_pk_fma_f32 v[236:237], v[214:215], v[52:53], v[222:223]
	v_pk_fma_f32 v[238:239], v[214:215], v[60:61], v[222:223]
	v_pk_fma_f32 v[234:235], v[210:211], v[64:65], v[234:235]
	v_pk_fma_f32 v[236:237], v[210:211], v[56:57], v[236:237]
	v_pk_fma_f32 v[238:239], v[210:211], v[52:53], v[238:239]
	v_pk_fma_f32 v[232:233], v[218:219], v[56:57], v[232:233]
	v_pk_fma_f32 v[234:235], v[218:219], v[52:53], v[234:235]
	v_pk_fma_f32 v[236:237], v[218:219], v[60:61], v[236:237]
	v_fmac_f32_dpp v232, v60, v210 row_ror:1 row_mask:0xf bank_mask:0xf
	v_fmac_f32_dpp v233, v61, v211 row_ror:1 row_mask:0xf bank_mask:0xf
	v_fmac_f32_dpp v238, v64, v218 row_ror:15 row_mask:0xf bank_mask:0xf
	v_fmac_f32_dpp v239, v65, v219 row_ror:15 row_mask:0xf bank_mask:0xf
	v_pk_mul_f32 v[64:65], v[232:233], v[240:241]
	v_pk_mul_f32 v[56:57], v[234:235], v[240:241]
	v_pk_mul_f32 v[52:53], v[236:237], v[240:241]
	v_pk_mul_f32 v[60:61], v[238:239], v[240:241]
	v_exp_f32_e32 v64, v64
	v_exp_f32_e32 v65, v65
	v_exp_f32_e32 v56, v56
	v_exp_f32_e32 v57, v57
	v_exp_f32_e32 v52, v52
	v_exp_f32_e32 v53, v53
	v_exp_f32_e32 v60, v60
	v_exp_f32_e32 v61, v61
	v_add_f32_e32 v64, 1.0, v64
	v_add_f32_e32 v65, 1.0, v65
	v_add_f32_e32 v56, 1.0, v56
	v_add_f32_e32 v57, 1.0, v57
	v_add_f32_e32 v52, 1.0, v52
	v_add_f32_e32 v53, 1.0, v53
	v_add_f32_e32 v60, 1.0, v60
	v_add_f32_e32 v61, 1.0, v61
	v_rcp_f32_e32 v64, v64
	v_rcp_f32_e32 v65, v65
	v_rcp_f32_e32 v56, v56
	v_rcp_f32_e32 v57, v57
	v_rcp_f32_e32 v52, v52
	v_rcp_f32_e32 v53, v53
	v_rcp_f32_e32 v60, v60
	v_rcp_f32_e32 v61, v61
	v_pk_mul_f32 v[64:65], v[232:233], v[64:65]
	v_pk_mul_f32 v[56:57], v[234:235], v[56:57]
	v_pk_mul_f32 v[52:53], v[236:237], v[52:53]
	v_pk_mul_f32 v[60:61], v[238:239], v[60:61]
	v_pk_fma_f32 v[46:47], v[46:47], v[224:225], v[184:185] op_sel_hi:[1,0,1]
	v_pk_fma_f32 v[48:49], v[48:49], v[224:225], v[186:187] op_sel_hi:[1,0,1]
	v_pk_fma_f32 v[38:39], v[38:39], v[224:225], v[184:185] op_sel:[0,1,0] op_sel_hi:[1,1,1]
	v_pk_fma_f32 v[40:41], v[40:41], v[224:225], v[186:187] op_sel:[0,1,0] op_sel_hi:[1,1,1]
	v_pk_fma_f32 v[34:35], v[34:35], v[226:227], v[184:185] op_sel_hi:[1,0,1]
	v_pk_fma_f32 v[36:37], v[36:37], v[226:227], v[186:187] op_sel_hi:[1,0,1]
	v_pk_fma_f32 v[42:43], v[42:43], v[226:227], v[184:185] op_sel:[0,1,0] op_sel_hi:[1,1,1]
	v_pk_fma_f32 v[44:45], v[44:45], v[226:227], v[186:187] op_sel:[0,1,0] op_sel_hi:[1,1,1]
	s_mov_b64 exec, s[4:5]
	global_store_dwordx4 v244, v[46:49], s[54:55] offset:16
	s_add_u32 s16, s54, 0x5800
; __device__ __forceinline__ unsigned cvt_pk_bf16_asm(float lo, float hi) { unsigned r; asm volatile("v_cvt_pk_bf16_f32 %0, %1, %2" : "=v"(r) : "v"(lo), "v"(hi)); return r; }
;     __device__ __forceinline__ void operator()(const f32x4 (&acc)[2][2][4][2], const Unit& u, int wr, int wc, int fr, int fq) const {
;     ...
;                     for (int m = 0; m < 4; ++m) { const f32x4 sp = (fr == 15 && m > 0) ? U[m > 0 ? m - 1 : 0] : U[m]; const f32x4 sn = (fr == 0 && m < 3) ? U[m < 3 ? m + 1 : 3] : U[m];
;                         f32x4 pv, nv;
; #pragma unroll
;                         for (int j = 0; j < 4; ++j) { pv[j] = __int_as_float(__builtin_amdgcn_update_dpp(0, __float_as_int(sp[j]), 0x121, 0xf, 0xf, false)); nv[j] = __int_as_float(__builtin_amdgcn_update_dpp(0, __float_as_int(sn[j]), 0x12F, 0xf, 0xf, false)); }
;                         const f32x4 R = prm[bj][1] * pv + prm[bj][2] * U[m] + prm[bj][3] * nv + prm[bj][4];
;                         if (bj == 1) {
; #pragma unroll
;                             for (int j = 0; j < 4; ++j) SG[m][j] = R[j] * __builtin_amdgcn_rcpf(1.0f + __expf(-R[j])); }
;                         else { const int r = row0 + ai * HALF + m * 16; const bool skip = (m == 0 && fr == 0) || (m == 3 && fr == 15);
;                             const f32x4 o = R * SG[m]; u32x2 w; w.x = cvt_pk_bf16_asm(o[0], o[1]); w.y = cvt_pk_bf16_asm(o[2], o[3]);
;                             if (!skip) *(u32x2*)(act + (size_t)r * FFD + u.pn * 128 + wc * 32 + 8 * fq + 4 * n) = w; } } } }
	s_addc_u32 s17, s55, 0
	global_store_dwordx4 v244, v[38:41], s[16:17] offset:16
	s_mov_b64 exec, s[6:7]
	s_add_u32 s56, s54, 0xb000
	s_addc_u32 s57, s55, 0
	global_store_dwordx4 v244, v[34:37], s[56:57] offset:16
	s_add_u32 s16, s54, 0x10800
	s_addc_u32 s17, s55, 0
	global_store_dwordx4 v244, v[42:45], s[16:17] offset:16
	s_mov_b64 exec, -1
	v_pk_fma_f32 v[232:233], v[192:193], v[46:47], v[200:201]
	v_pk_fma_f32 v[234:235], v[192:193], v[38:39], v[200:201]
	v_pk_fma_f32 v[236:237], v[192:193], v[34:35], v[200:201]
	v_pk_fma_f32 v[238:239], v[192:193], v[42:43], v[200:201]
	v_pk_fma_f32 v[234:235], v[188:189], v[46:47], v[234:235]
	v_pk_fma_f32 v[236:237], v[188:189], v[38:39], v[236:237]
	v_pk_fma_f32 v[238:239], v[188:189], v[34:35], v[238:239]
	v_pk_fma_f32 v[232:233], v[196:197], v[38:39], v[232:233]
	v_pk_fma_f32 v[234:235], v[196:197], v[34:35], v[234:235]
	v_pk_fma_f32 v[236:237], v[196:197], v[42:43], v[236:237]
	v_fmac_f32_dpp v232, v42, v188 row_ror:1 row_mask:0xf bank_mask:0xf
	v_fmac_f32_dpp v233, v43, v189 row_ror:1 row_mask:0xf bank_mask:0xf
	v_fmac_f32_dpp v238, v46, v196 row_ror:15 row_mask:0xf bank_mask:0xf
	v_fmac_f32_dpp v239, v47, v197 row_ror:15 row_mask:0xf bank_mask:0xf
	v_pk_mul_f32 v[232:233], v[232:233], v[62:63]
	v_pk_mul_f32 v[234:235], v[234:235], v[54:55]
	v_pk_mul_f32 v[236:237], v[236:237], v[50:51]
	v_pk_mul_f32 v[238:239], v[238:239], v[58:59]
	v_cvt_pk_bf16_f32 v148, v232, v233
	v_cvt_pk_bf16_f32 v136, v234, v235
	v_cvt_pk_bf16_f32 v132, v236, v237
	v_cvt_pk_bf16_f32 v144, v238, v239
	v_pk_fma_f32 v[232:233], v[194:195], v[48:49], v[202:203]
	v_pk_fma_f32 v[234:235], v[194:195], v[40:41], v[202:203]
	v_pk_fma_f32 v[236:237], v[194:195], v[36:37], v[202:203]
	v_pk_fma_f32 v[238:239], v[194:195], v[44:45], v[202:203]
	v_pk_fma_f32 v[234:235], v[190:191], v[48:49], v[234:235]
	v_pk_fma_f32 v[236:237], v[190:191], v[40:41], v[236:237]
	v_pk_fma_f32 v[238:239], v[190:191], v[36:37], v[238:239]
	v_pk_fma_f32 v[232:233], v[198:199], v[40:41], v[232:233]
	v_pk_fma_f32 v[234:235], v[198:199], v[36:37], v[234:235]
	v_pk_fma_f32 v[236:237], v[198:199], v[44:45], v[236:237]
	v_fmac_f32_dpp v232, v44, v190 row_ror:1 row_mask:0xf bank_mask:0xf
	v_fmac_f32_dpp v233, v45, v191 row_ror:1 row_mask:0xf bank_mask:0xf
	v_fmac_f32_dpp v238, v48, v198 row_ror:15 row_mask:0xf bank_mask:0xf
	v_fmac_f32_dpp v239, v49, v199 row_ror:15 row_mask:0xf bank_mask:0xf
	v_pk_mul_f32 v[232:233], v[232:233], v[64:65]
	v_pk_mul_f32 v[234:235], v[234:235], v[56:57]
	v_pk_mul_f32 v[236:237], v[236:237], v[52:53]
	v_pk_mul_f32 v[238:239], v[238:239], v[60:61]
	v_cvt_pk_bf16_f32 v149, v232, v233
	v_cvt_pk_bf16_f32 v137, v234, v235
	v_cvt_pk_bf16_f32 v133, v236, v237
	v_cvt_pk_bf16_f32 v145, v238, v239
	s_add_u32 s16, s74, 0x0
	s_addc_u32 s17, s75, 0
	s_not_b64 exec, s[4:5]
	global_store_dwordx4 v245, v[146:149], s[16:17]
	s_mov_b64 exec, -1
	s_add_u32 s16, s74, 0x1600
	s_addc_u32 s17, s75, 0
	global_store_dwordx4 v245, v[134:137], s[16:17]
	s_add_u32 s16, s74, 0x2c00
	s_addc_u32 s17, s75, 0
	global_store_dwordx4 v245, v[130:133], s[16:17]
	s_add_u32 s16, s74, 0x4200
	s_addc_u32 s17, s75, 0
	s_not_b64 exec, s[6:7]
	global_store_dwordx4 v245, v[142:145], s[16:17]
	s_mov_b64 exec, -1
	s_add_u32 s54, s54, 0x2c000
	s_addc_u32 s55, s55, 0
	v_pk_fma_f32 v[30:31], v[30:31], v[228:229], v[204:205] op_sel_hi:[1,0,1]
	v_pk_fma_f32 v[32:33], v[32:33], v[228:229], v[206:207] op_sel_hi:[1,0,1]
	v_pk_fma_f32 v[26:27], v[26:27], v[228:229], v[204:205] op_sel:[0,1,0] op_sel_hi:[1,1,1]
	v_pk_fma_f32 v[28:29], v[28:29], v[228:229], v[206:207] op_sel:[0,1,0] op_sel_hi:[1,1,1]
	v_pk_fma_f32 v[18:19], v[18:19], v[230:231], v[204:205] op_sel_hi:[1,0,1]
	v_pk_fma_f32 v[20:21], v[20:21], v[230:231], v[206:207] op_sel_hi:[1,0,1]
	v_pk_fma_f32 v[22:23], v[22:23], v[230:231], v[204:205] op_sel:[0,1,0] op_sel_hi:[1,1,1]
	v_pk_fma_f32 v[24:25], v[24:25], v[230:231], v[206:207] op_sel:[0,1,0] op_sel_hi:[1,1,1]
	s_mov_b64 exec, s[4:5]
	global_store_dwordx4 v244, v[30:33], s[54:55] offset:528
	s_add_u32 s16, s54, 0x5800
	s_addc_u32 s17, s55, 0
	global_store_dwordx4 v244, v[26:29], s[16:17] offset:528
	s_mov_b64 exec, s[6:7]
	s_add_u32 s56, s54, 0xb000
	s_addc_u32 s57, s55, 0
	global_store_dwordx4 v244, v[18:21], s[56:57] offset:528
	s_add_u32 s16, s54, 0x10800
	s_addc_u32 s17, s55, 0
	global_store_dwordx4 v244, v[22:25], s[16:17] offset:528
	s_mov_b64 exec, -1
	v_pk_fma_f32 v[232:233], v[212:213], v[30:31], v[220:221]
	v_pk_fma_f32 v[234:235], v[212:213], v[26:27], v[220:221]
	v_pk_fma_f32 v[236:237], v[212:213], v[18:19], v[220:221]
	v_pk_fma_f32 v[238:239], v[212:213], v[22:23], v[220:221]
	v_pk_fma_f32 v[234:235], v[208:209], v[30:31], v[234:235]
	v_pk_fma_f32 v[236:237], v[208:209], v[26:27], v[236:237]
	v_pk_fma_f32 v[238:239], v[208:209], v[18:19], v[238:239]
	v_pk_fma_f32 v[232:233], v[216:217], v[26:27], v[232:233]
	v_pk_fma_f32 v[234:235], v[216:217], v[18:19], v[234:235]
	v_pk_fma_f32 v[236:237], v[216:217], v[22:23], v[236:237]
	v_fmac_f32_dpp v232, v22, v208 row_ror:1 row_mask:0xf bank_mask:0xf
	v_fmac_f32_dpp v233, v23, v209 row_ror:1 row_mask:0xf bank_mask:0xf
	v_fmac_f32_dpp v238, v30, v216 row_ror:15 row_mask:0xf bank_mask:0xf
	v_fmac_f32_dpp v239, v31, v217 row_ror:15 row_mask:0xf bank_mask:0xf
	v_pk_mul_f32 v[30:31], v[232:233], v[240:241]
	v_pk_mul_f32 v[26:27], v[234:235], v[240:241]
	v_pk_mul_f32 v[18:19], v[236:237], v[240:241]
	v_pk_mul_f32 v[22:23], v[238:239], v[240:241]
	v_exp_f32_e32 v30, v30
	v_exp_f32_e32 v31, v31
	v_exp_f32_e32 v26, v26
	v_exp_f32_e32 v27, v27
	v_exp_f32_e32 v18, v18
	v_exp_f32_e32 v19, v19
	v_exp_f32_e32 v22, v22
	v_exp_f32_e32 v23, v23
; __device__ __forceinline__ unsigned cvt_pk_bf16_asm(float lo, float hi) { unsigned r; asm volatile("v_cvt_pk_bf16_f32 %0, %1, %2" : "=v"(r) : "v"(lo), "v"(hi)); return r; }
;     __device__ __forceinline__ void operator()(const f32x4 (&acc)[2][2][4][2], const Unit& u, int wr, int wc, int fr, int fq) const {
;     ...
;                     for (int m = 0; m < 4; ++m) { const f32x4 sp = (fr == 15 && m > 0) ? U[m > 0 ? m - 1 : 0] : U[m]; const f32x4 sn = (fr == 0 && m < 3) ? U[m < 3 ? m + 1 : 3] : U[m];
;                         f32x4 pv, nv;
; #pragma unroll
;                         for (int j = 0; j < 4; ++j) { pv[j] = __int_as_float(__builtin_amdgcn_update_dpp(0, __float_as_int(sp[j]), 0x121, 0xf, 0xf, false)); nv[j] = __int_as_float(__builtin_amdgcn_update_dpp(0, __float_as_int(sn[j]), 0x12F, 0xf, 0xf, false)); }
;                         const f32x4 R = prm[bj][1] * pv + prm[bj][2] * U[m] + prm[bj][3] * nv + prm[bj][4];
;                         if (bj == 1) {
; #pragma unroll
;                             for (int j = 0; j < 4; ++j) SG[m][j] = R[j] * __builtin_amdgcn_rcpf(1.0f + __expf(-R[j])); }
;                         else { const int r = row0 + ai * HALF + m * 16; const bool skip = (m == 0 && fr == 0) || (m == 3 && fr == 15);
;                             const f32x4 o = R * SG[m]; u32x2 w; w.x = cvt_pk_bf16_asm(o[0], o[1]); w.y = cvt_pk_bf16_asm(o[2], o[3]);
;                             if (!skip) *(u32x2*)(act + (size_t)r * FFD + u.pn * 128 + wc * 32 + 8 * fq + 4 * n) = w; } } } }
	v_add_f32_e32 v30, 1.0, v30
	v_add_f32_e32 v31, 1.0, v31
	v_add_f32_e32 v26, 1.0, v26
	v_add_f32_e32 v27, 1.0, v27
	v_add_f32_e32 v18, 1.0, v18
	v_add_f32_e32 v19, 1.0, v19
	v_add_f32_e32 v22, 1.0, v22
	v_add_f32_e32 v23, 1.0, v23
	v_rcp_f32_e32 v30, v30
	v_rcp_f32_e32 v31, v31
	v_rcp_f32_e32 v26, v26
	v_rcp_f32_e32 v27, v27
	v_rcp_f32_e32 v18, v18
	v_rcp_f32_e32 v19, v19
	v_rcp_f32_e32 v22, v22
	v_rcp_f32_e32 v23, v23
	v_pk_mul_f32 v[30:31], v[232:233], v[30:31]
	v_pk_mul_f32 v[26:27], v[234:235], v[26:27]
	v_pk_mul_f32 v[18:19], v[236:237], v[18:19]
	v_pk_mul_f32 v[22:23], v[238:239], v[22:23]
	v_pk_fma_f32 v[232:233], v[214:215], v[32:33], v[222:223]
	v_pk_fma_f32 v[234:235], v[214:215], v[28:29], v[222:223]
	v_pk_fma_f32 v[236:237], v[214:215], v[20:21], v[222:223]
	v_pk_fma_f32 v[238:239], v[214:215], v[24:25], v[222:223]
	v_pk_fma_f32 v[234:235], v[210:211], v[32:33], v[234:235]
	v_pk_fma_f32 v[236:237], v[210:211], v[28:29], v[236:237]
	v_pk_fma_f32 v[238:239], v[210:211], v[20:21], v[238:239]
	v_pk_fma_f32 v[232:233], v[218:219], v[28:29], v[232:233]
	v_pk_fma_f32 v[234:235], v[218:219], v[20:21], v[234:235]
	v_pk_fma_f32 v[236:237], v[218:219], v[24:25], v[236:237]
	v_fmac_f32_dpp v232, v24, v210 row_ror:1 row_mask:0xf bank_mask:0xf
	v_fmac_f32_dpp v233, v25, v211 row_ror:1 row_mask:0xf bank_mask:0xf
	v_fmac_f32_dpp v238, v32, v218 row_ror:15 row_mask:0xf bank_mask:0xf
	v_fmac_f32_dpp v239, v33, v219 row_ror:15 row_mask:0xf bank_mask:0xf
	v_pk_mul_f32 v[32:33], v[232:233], v[240:241]
	v_pk_mul_f32 v[28:29], v[234:235], v[240:241]
	v_pk_mul_f32 v[20:21], v[236:237], v[240:241]
	v_pk_mul_f32 v[24:25], v[238:239], v[240:241]
	v_exp_f32_e32 v32, v32
	v_exp_f32_e32 v33, v33
	v_exp_f32_e32 v28, v28
	v_exp_f32_e32 v29, v29
	v_exp_f32_e32 v20, v20
	v_exp_f32_e32 v21, v21
	v_exp_f32_e32 v24, v24
	v_exp_f32_e32 v25, v25
	v_add_f32_e32 v32, 1.0, v32
	v_add_f32_e32 v33, 1.0, v33
	v_add_f32_e32 v28, 1.0, v28
	v_add_f32_e32 v29, 1.0, v29
	v_add_f32_e32 v20, 1.0, v20
	v_add_f32_e32 v21, 1.0, v21
	v_add_f32_e32 v24, 1.0, v24
	v_add_f32_e32 v25, 1.0, v25
	v_rcp_f32_e32 v32, v32
	v_rcp_f32_e32 v33, v33
	v_rcp_f32_e32 v28, v28
	v_rcp_f32_e32 v29, v29
	v_rcp_f32_e32 v20, v20
	v_rcp_f32_e32 v21, v21
	v_rcp_f32_e32 v24, v24
	v_rcp_f32_e32 v25, v25
	v_pk_mul_f32 v[32:33], v[232:233], v[32:33]
	v_pk_mul_f32 v[28:29], v[234:235], v[28:29]
	v_pk_mul_f32 v[20:21], v[236:237], v[20:21]
	v_pk_mul_f32 v[24:25], v[238:239], v[24:25]
	v_pk_fma_f32 v[14:15], v[14:15], v[228:229], v[184:185] op_sel_hi:[1,0,1]
	v_pk_fma_f32 v[16:17], v[16:17], v[228:229], v[186:187] op_sel_hi:[1,0,1]
	v_pk_fma_f32 v[6:7], v[6:7], v[228:229], v[184:185] op_sel:[0,1,0] op_sel_hi:[1,1,1]
	v_pk_fma_f32 v[8:9], v[8:9], v[228:229], v[186:187] op_sel:[0,1,0] op_sel_hi:[1,1,1]
	v_pk_fma_f32 v[2:3], v[2:3], v[230:231], v[184:185] op_sel_hi:[1,0,1]
	v_pk_fma_f32 v[4:5], v[4:5], v[230:231], v[186:187] op_sel_hi:[1,0,1]
	v_pk_fma_f32 v[10:11], v[10:11], v[230:231], v[184:185] op_sel:[0,1,0] op_sel_hi:[1,1,1]
	v_pk_fma_f32 v[12:13], v[12:13], v[230:231], v[186:187] op_sel:[0,1,0] op_sel_hi:[1,1,1]
	s_mov_b64 exec, s[4:5]
	global_store_dwordx4 v244, v[14:17], s[54:55] offset:16
	s_add_u32 s16, s54, 0x5800
	s_addc_u32 s17, s55, 0
	global_store_dwordx4 v244, v[6:9], s[16:17] offset:16
	s_mov_b64 exec, s[6:7]
	s_add_u32 s56, s54, 0xb000
	s_addc_u32 s57, s55, 0
	global_store_dwordx4 v244, v[2:5], s[56:57] offset:16
	s_add_u32 s16, s54, 0x10800
	s_addc_u32 s17, s55, 0
	global_store_dwordx4 v244, v[10:13], s[16:17] offset:16
	s_mov_b64 exec, -1
	v_pk_fma_f32 v[232:233], v[192:193], v[14:15], v[200:201]
	v_pk_fma_f32 v[234:235], v[192:193], v[6:7], v[200:201]
	v_pk_fma_f32 v[236:237], v[192:193], v[2:3], v[200:201]
	v_pk_fma_f32 v[238:239], v[192:193], v[10:11], v[200:201]
	v_pk_fma_f32 v[234:235], v[188:189], v[14:15], v[234:235]
	v_pk_fma_f32 v[236:237], v[188:189], v[6:7], v[236:237]
	v_pk_fma_f32 v[238:239], v[188:189], v[2:3], v[238:239]
	v_pk_fma_f32 v[232:233], v[196:197], v[6:7], v[232:233]
	v_pk_fma_f32 v[234:235], v[196:197], v[2:3], v[234:235]
	v_pk_fma_f32 v[236:237], v[196:197], v[10:11], v[236:237]
	v_fmac_f32_dpp v232, v10, v188 row_ror:1 row_mask:0xf bank_mask:0xf
	v_fmac_f32_dpp v233, v11, v189 row_ror:1 row_mask:0xf bank_mask:0xf
	v_fmac_f32_dpp v238, v14, v196 row_ror:15 row_mask:0xf bank_mask:0xf
	v_fmac_f32_dpp v239, v15, v197 row_ror:15 row_mask:0xf bank_mask:0xf
	v_pk_mul_f32 v[232:233], v[232:233], v[30:31]
	v_pk_mul_f32 v[234:235], v[234:235], v[26:27]
	v_pk_mul_f32 v[236:237], v[236:237], v[18:19]
	v_pk_mul_f32 v[238:239], v[238:239], v[22:23]
	v_cvt_pk_bf16_f32 v80, v232, v233
	v_cvt_pk_bf16_f32 v72, v234, v235
	v_cvt_pk_bf16_f32 v68, v236, v237
	v_cvt_pk_bf16_f32 v76, v238, v239
	v_pk_fma_f32 v[232:233], v[194:195], v[16:17], v[202:203]
	v_pk_fma_f32 v[234:235], v[194:195], v[8:9], v[202:203]
	v_pk_fma_f32 v[236:237], v[194:195], v[4:5], v[202:203]
	v_pk_fma_f32 v[238:239], v[194:195], v[12:13], v[202:203]
	v_pk_fma_f32 v[234:235], v[190:191], v[16:17], v[234:235]
	v_pk_fma_f32 v[236:237], v[190:191], v[8:9], v[236:237]
	v_pk_fma_f32 v[238:239], v[190:191], v[4:5], v[238:239]
	v_pk_fma_f32 v[232:233], v[198:199], v[8:9], v[232:233]
	v_pk_fma_f32 v[234:235], v[198:199], v[4:5], v[234:235]
	v_pk_fma_f32 v[236:237], v[198:199], v[12:13], v[236:237]
	v_fmac_f32_dpp v232, v12, v190 row_ror:1 row_mask:0xf bank_mask:0xf
	v_fmac_f32_dpp v233, v13, v191 row_ror:1 row_mask:0xf bank_mask:0xf
	v_fmac_f32_dpp v238, v16, v198 row_ror:15 row_mask:0xf bank_mask:0xf
	v_fmac_f32_dpp v239, v17, v199 row_ror:15 row_mask:0xf bank_mask:0xf
	v_pk_mul_f32 v[232:233], v[232:233], v[32:33]
	v_pk_mul_f32 v[234:235], v[234:235], v[28:29]
	v_pk_mul_f32 v[236:237], v[236:237], v[20:21]
	v_pk_mul_f32 v[238:239], v[238:239], v[24:25]
	v_cvt_pk_bf16_f32 v81, v232, v233
	v_cvt_pk_bf16_f32 v73, v234, v235
	v_cvt_pk_bf16_f32 v69, v236, v237
	v_cvt_pk_bf16_f32 v77, v238, v239
	s_add_u32 s16, s74, 0xb0000
	s_addc_u32 s17, s75, 0
	s_not_b64 exec, s[4:5]
	global_store_dwordx4 v245, v[78:81], s[16:17]
	s_mov_b64 exec, -1
	s_add_u32 s16, s74, 0xb1600
	s_addc_u32 s17, s75, 0
	global_store_dwordx4 v245, v[70:73], s[16:17]
	s_add_u32 s16, s74, 0xb2c00
	s_addc_u32 s17, s75, 0
	global_store_dwordx4 v245, v[66:69], s[16:17]
	s_add_u32 s16, s74, 0xb4200
	s_addc_u32 s17, s75, 0
	s_not_b64 exec, s[6:7]
	global_store_dwordx4 v245, v[74:77], s[16:17]
	s_mov_b64 exec, -1
	s_branch .LBB0_451
